# MLA: waves 4-7 meet the barrier behind their 3rd PV MFMA (tile writes in front of it)
# speedup vs baseline: 1.0033x; 1.0033x over previous
; __device__ __forceinline__ void finishSM9(f32x16& p0, f32x16& p1, float alpha, float& l_reg, v8i32& p8) {
; #pragma unroll
;   for (int r = 0; r < 16; ++r) { p0[r] = __builtin_amdgcn_exp2f(p0[r]); p1[r] = __builtin_amdgcn_exp2f(p1[r]); }
;   float ps = 0;
; #pragma unroll
;   for (int r = 0; r < 16; ++r) ps += p0[r];
; #pragma unroll
;   for (int r = 0; r < 16; ++r) ps += p1[r];
;   { auto rr = __builtin_amdgcn_permlane32_swap(__float_as_uint(ps), __float_as_uint(ps), false, false);
;     ps = __uint_as_float(rr[0]) + __uint_as_float(rr[1]); }
;   l_reg = l_reg * alpha + ps;
; #pragma unroll
;   for (int g = 0; g < 4; ++g) {
;     int w = __builtin_amdgcn_cvt_pk_fp8_f32(p0[4 * g], p0[4 * g + 1], 0, false); p8[g] = __builtin_amdgcn_cvt_pk_fp8_f32(p0[4 * g + 2], p0[4 * g + 3], w, true);
;     int u = __builtin_amdgcn_cvt_pk_fp8_f32(p1[4 * g], p1[4 * g + 1], 0, false); p8[4 + g] = __builtin_amdgcn_cvt_pk_fp8_f32(p1[4 * g + 2], p1[4 * g + 3], u, true); }
; }
; __device__ __forceinline__ void pv8(f32x16* o, const char* Vt, const v8i32 p8, int r32, int hi) {
;   const int sw = (r32 >> 2) & 3, a0 = r32 * 64 + (((hi * 2) ^ sw) << 4), a1 = r32 * 64 + (((hi * 2 + 1) ^ sw) << 4);
; #pragma unroll
;   for (int d0 = 0; d0 < 4; ++d0) {
;     const v8i32 vf = cat8(*reinterpret_cast<const v4i32*>(Vt + d0 * 2048 + a0), *reinterpret_cast<const v4i32*>(Vt + d0 * 2048 + a1));
;     o[d0] = __builtin_amdgcn_mfma_scale_f32_32x32x64_f8f6f4(p8, vf, o[d0], 0, 0, 0, 127, 0, 127); }
; }
; __device__ __forceinline__ void qkt9(f32x16& p0, f32x16& p1, const char* Kn, const char* Kr, const v8i32* qf, const float init, int r32, int hi) {
; #pragma unroll
;   for (int r = 0; r < 16; ++r) { p0[r] = init; p1[r] = init; }
; #pragma unroll
;   for (int s = 0; s < 2; ++s) { const int c0 = s * 4 + hi * 2;
;     const v8i32 a0 = cat8(*reinterpret_cast<const v4i32*>(Kn + KN8SW(r32, c0)), *reinterpret_cast<const v4i32*>(Kn + KN8SW(r32, c0 + 1)));
;     const v8i32 a1 = cat8(*reinterpret_cast<const v4i32*>(Kn + 4096 + KN8SW(r32, c0)), *reinterpret_cast<const v4i32*>(Kn + 4096 + KN8SW(r32, c0 + 1)));
;     p0 = __builtin_amdgcn_mfma_scale_f32_32x32x64_f8f6f4(a0, qf[s], p0, 0, 0, 0, 127, 0, 124);
;     p1 = __builtin_amdgcn_mfma_scale_f32_32x32x64_f8f6f4(a1, qf[s], p1, 0, 0, 0, 127, 0, 124); }
;   { const int c0 = hi * 2;
.Lmla_stag_loop:
	ds_read_b128 v[114:117], v215 offset:24576
	ds_read_b128 v[118:121], v216 offset:24576
	ds_read_b128 v[222:225], v215 offset:28672
	ds_read_b128 v[226:229], v216 offset:28672
	v_exp_f32_e32 v0, v82
	v_exp_f32_e32 v177, v83
	v_exp_f32_e32 v179, v84
	v_exp_f32_e32 v254, v85
	v_add_f32_e32 v219, v0, v177
	v_cvt_pk_fp8_f32 v246, v0, v177
	v_add_f32_e32 v219, v179, v219
	v_add_f32_e32 v219, v254, v219
	v_cvt_pk_fp8_f32 v246, v179, v254 op_sel:[0,0,1]
	s_waitcnt lgkmcnt(2)
	v_mfma_scale_f32_32x32x64_f8f6f4 v[114:129], v[114:121], v[146:153], v[230:245], v194, v193 op_sel_hi:[0,0,0]
	v_exp_f32_e32 v0, v86
	v_exp_f32_e32 v177, v87
	v_exp_f32_e32 v179, v88
	v_exp_f32_e32 v254, v89
	v_add_f32_e32 v219, v0, v219
	v_add_f32_e32 v219, v177, v219
	v_cvt_pk_fp8_f32 v247, v0, v177
	v_add_f32_e32 v219, v179, v219
	v_add_f32_e32 v219, v254, v219
	v_cvt_pk_fp8_f32 v247, v179, v254 op_sel:[0,0,1]
	ds_read_b128 v[82:85], v213 offset:24576
	ds_read_b128 v[86:89], v214 offset:24576
	s_waitcnt lgkmcnt(2)
	v_mfma_scale_f32_32x32x64_f8f6f4 v[98:113], v[222:229], v[146:153], v[230:245], v194, v193 op_sel_hi:[0,0,0]
	ds_read_b128 v[222:225], v213 offset:28672
	ds_read_b128 v[226:229], v214 offset:28672
	v_exp_f32_e32 v0, v90
	v_exp_f32_e32 v177, v91
	v_exp_f32_e32 v179, v92
	v_exp_f32_e32 v254, v93
	v_add_f32_e32 v219, v0, v219
	v_add_f32_e32 v219, v177, v219
	v_cvt_pk_fp8_f32 v248, v0, v177
	v_add_f32_e32 v219, v179, v219
	v_add_f32_e32 v219, v254, v219
	v_cvt_pk_fp8_f32 v248, v179, v254 op_sel:[0,0,1]
	v_exp_f32_e32 v0, v94
	v_exp_f32_e32 v177, v95
	v_exp_f32_e32 v179, v96
	v_exp_f32_e32 v254, v97
	v_add_f32_e32 v219, v0, v219
	v_add_f32_e32 v219, v177, v219
	v_cvt_pk_fp8_f32 v249, v0, v177
	v_add_f32_e32 v219, v179, v219
	v_add_f32_e32 v219, v254, v219
	v_cvt_pk_fp8_f32 v249, v179, v254 op_sel:[0,0,1]
	ds_read_b128 v[90:93], v185 offset:36864
	ds_read_b128 v[94:97], v186 offset:36864
	s_waitcnt lgkmcnt(4)
	v_mfma_scale_f32_32x32x64_f8f6f4 v[114:129], v[82:89], v[138:145], v[114:129], v194, v193 op_sel_hi:[0,0,0]
	v_exp_f32_e32 v0, v66
	v_exp_f32_e32 v177, v67
	v_exp_f32_e32 v179, v68
	v_exp_f32_e32 v254, v69
	v_add_f32_e32 v219, v0, v219
	v_add_f32_e32 v219, v177, v219
	v_cvt_pk_fp8_f32 v250, v0, v177
	v_add_f32_e32 v219, v179, v219
	v_add_f32_e32 v219, v254, v219
	v_cvt_pk_fp8_f32 v250, v179, v254 op_sel:[0,0,1]
	s_waitcnt lgkmcnt(2)
	v_mfma_scale_f32_32x32x64_f8f6f4 v[98:113], v[222:229], v[138:145], v[98:113], v194, v193 op_sel_hi:[0,0,0]
	ds_read_b128 v[222:225], v185 offset:38912
	ds_read_b128 v[226:229], v186 offset:38912
	v_exp_f32_e32 v0, v70
	v_exp_f32_e32 v177, v71
	v_exp_f32_e32 v179, v72
	v_exp_f32_e32 v254, v73
	v_add_f32_e32 v219, v0, v219
	v_add_f32_e32 v219, v177, v219
	v_cvt_pk_fp8_f32 v251, v0, v177
	v_add_f32_e32 v219, v179, v219
	v_add_f32_e32 v219, v254, v219
	v_cvt_pk_fp8_f32 v251, v179, v254 op_sel:[0,0,1]
	v_exp_f32_e32 v0, v74
	v_exp_f32_e32 v177, v75
	v_exp_f32_e32 v179, v76
	v_exp_f32_e32 v254, v77
	v_add_f32_e32 v219, v0, v219
	v_add_f32_e32 v219, v177, v219
	v_cvt_pk_fp8_f32 v252, v0, v177
	v_add_f32_e32 v219, v179, v219
	v_add_f32_e32 v219, v254, v219
	v_cvt_pk_fp8_f32 v252, v179, v254 op_sel:[0,0,1]
	s_waitcnt lgkmcnt(2)
	v_mfma_scale_f32_32x32x64_f8f6f4 v[114:129], v[90:97], v[130:137], v[114:129], v194, v193 op_sel_hi:[0,0,0]
	v_exp_f32_e32 v0, v78
	v_exp_f32_e32 v177, v79
	v_exp_f32_e32 v179, v80
	v_exp_f32_e32 v254, v81
	v_add_f32_e32 v219, v0, v219
	v_add_f32_e32 v219, v177, v219
	v_cvt_pk_fp8_f32 v253, v0, v177
	v_add_f32_e32 v219, v179, v219
	v_add_f32_e32 v219, v254, v219
	v_cvt_pk_fp8_f32 v253, v179, v254 op_sel:[0,0,1]
	ds_read_b128 v[90:93], v185 offset:0
	ds_read_b128 v[94:97], v186 offset:0
	ds_read_b128 v[82:85], v185 offset:2048
	ds_read_b128 v[86:89], v186 offset:2048
	ds_read_b128 v[74:77], v185 offset:4096
	ds_read_b128 v[78:81], v186 offset:4096
	ds_read_b128 v[66:69], v185 offset:6144
	ds_read_b128 v[70:73], v186 offset:6144
	s_waitcnt lgkmcnt(8)
	v_mfma_scale_f32_32x32x64_f8f6f4 v[98:113], v[222:229], v[130:137], v[98:113], v194, v193 op_sel_hi:[0,0,0]
	v_mov_b32_e32 v0, v219
	s_nop 1
	v_permlane32_swap_b32_e32 v219, v0
	v_add_f32_e32 v219, v219, v0
	v_fma_f32 v209, v209, v218, v219
	v_max_f32_e32 v177, v114, v115
	v_max3_f32 v177, v177, v116, v117
	v_max3_f32 v177, v177, v118, v119
	v_max3_f32 v177, v177, v120, v121
	v_max3_f32 v177, v177, v122, v123
	v_max3_f32 v177, v177, v124, v125
	v_max3_f32 v177, v177, v126, v127
	v_max3_f32 v177, v177, v128, v129
	s_waitcnt lgkmcnt(6)
	v_mfma_scale_f32_32x32x64_f8f6f4 v[50:65], v[246:253], v[90:97], v[50:65], v194, v194 op_sel_hi:[0,0,0]
	s_waitcnt lgkmcnt(4)
	v_mfma_scale_f32_32x32x64_f8f6f4 v[34:49], v[246:253], v[82:89], v[34:49], v194, v194 op_sel_hi:[0,0,0]
	s_waitcnt vmcnt(0)
	ds_write_b128 v210, v[158:161] offset:43008
	ds_write_b128 v211, v[162:165] offset:51200
	s_waitcnt lgkmcnt(4)
	v_mfma_scale_f32_32x32x64_f8f6f4 v[18:33], v[246:253], v[74:81], v[18:33], v194, v194 op_sel_hi:[0,0,0]
	s_waitcnt lgkmcnt(0)
	s_barrier
	global_load_dwordx4 v[158:161], v176, s[18:19]
	global_load_dwordx4 v[162:165], v178, s[16:17]
	v_add_u32_e32 v176, 0x2000, v176
	v_add_u32_e32 v178, 0x20000, v178
	s_waitcnt lgkmcnt(0)
	v_mfma_scale_f32_32x32x64_f8f6f4 v[2:17], v[246:253], v[66:73], v[2:17], v194, v194 op_sel_hi:[0,0,0]
	v_max_f32_e32 v0, v98, v99
	v_max3_f32 v0, v0, v100, v101
	v_max3_f32 v0, v0, v102, v103
	v_max3_f32 v0, v0, v104, v105
	v_max3_f32 v0, v0, v106, v107
	v_max3_f32 v0, v0, v108, v109
	v_max3_f32 v0, v0, v110, v111
	v_max3_f32 v0, v0, v112, v113
	v_max_f32_e32 v177, v177, v0
	v_mov_b32_e32 v0, v177
	v_mov_b32_e32 v221, 1.0
	s_nop 0
	v_permlane32_swap_b32_e32 v177, v0
	v_max_f32_e32 v177, v177, v0
	v_cmp_ge_f32_e32 vcc, s90, v177
	s_cmp_eq_u64 vcc, exec
	s_cbranch_scc0 .Lmla_s0_newmax
; __device__ __forceinline__ void finishSM9(f32x16& p0, f32x16& p1, float alpha, float& l_reg, v8i32& p8) {
; #pragma unroll
;   for (int r = 0; r < 16; ++r) { p0[r] = __builtin_amdgcn_exp2f(p0[r]); p1[r] = __builtin_amdgcn_exp2f(p1[r]); }
;   float ps = 0;
; #pragma unroll
;   for (int r = 0; r < 16; ++r) ps += p0[r];
; #pragma unroll
;   for (int r = 0; r < 16; ++r) ps += p1[r];
;   { auto rr = __builtin_amdgcn_permlane32_swap(__float_as_uint(ps), __float_as_uint(ps), false, false);
;     ps = __uint_as_float(rr[0]) + __uint_as_float(rr[1]); }
;   l_reg = l_reg * alpha + ps;
; #pragma unroll
;   for (int g = 0; g < 4; ++g) {
;     int w = __builtin_amdgcn_cvt_pk_fp8_f32(p0[4 * g], p0[4 * g + 1], 0, false); p8[g] = __builtin_amdgcn_cvt_pk_fp8_f32(p0[4 * g + 2], p0[4 * g + 3], w, true);
;     int u = __builtin_amdgcn_cvt_pk_fp8_f32(p1[4 * g], p1[4 * g + 1], 0, false); p8[4 + g] = __builtin_amdgcn_cvt_pk_fp8_f32(p1[4 * g + 2], p1[4 * g + 3], u, true); }
; }
; __device__ __forceinline__ void pv8(f32x16* o, const char* Vt, const v8i32 p8, int r32, int hi) {
;   const int sw = (r32 >> 2) & 3, a0 = r32 * 64 + (((hi * 2) ^ sw) << 4), a1 = r32 * 64 + (((hi * 2 + 1) ^ sw) << 4);
; #pragma unroll
;   for (int d0 = 0; d0 < 4; ++d0) {
;     const v8i32 vf = cat8(*reinterpret_cast<const v4i32*>(Vt + d0 * 2048 + a0), *reinterpret_cast<const v4i32*>(Vt + d0 * 2048 + a1));
;     o[d0] = __builtin_amdgcn_mfma_scale_f32_32x32x64_f8f6f4(p8, vf, o[d0], 0, 0, 0, 127, 0, 127); }
; }
; __device__ __forceinline__ void qkt9(f32x16& p0, f32x16& p1, const char* Kn, const char* Kr, const v8i32* qf, const float init, int r32, int hi) {
; #pragma unroll
;   for (int r = 0; r < 16; ++r) { p0[r] = init; p1[r] = init; }
; #pragma unroll
;   for (int s = 0; s < 2; ++s) { const int c0 = s * 4 + hi * 2;
;     const v8i32 a0 = cat8(*reinterpret_cast<const v4i32*>(Kn + KN8SW(r32, c0)), *reinterpret_cast<const v4i32*>(Kn + KN8SW(r32, c0 + 1)));
;     const v8i32 a1 = cat8(*reinterpret_cast<const v4i32*>(Kn + 4096 + KN8SW(r32, c0)), *reinterpret_cast<const v4i32*>(Kn + 4096 + KN8SW(r32, c0 + 1)));
;     p0 = __builtin_amdgcn_mfma_scale_f32_32x32x64_f8f6f4(a0, qf[s], p0, 0, 0, 0, 127, 0, 124);
;     p1 = __builtin_amdgcn_mfma_scale_f32_32x32x64_f8f6f4(a1, qf[s], p1, 0, 0, 0, 127, 0, 124); }
;   { const int c0 = hi * 2;
.Lmla_s0_cont:
	ds_read_b128 v[82:85], v215 offset:51200
	ds_read_b128 v[86:89], v216 offset:51200
	ds_read_b128 v[222:225], v215 offset:55296
	ds_read_b128 v[226:229], v216 offset:55296
	v_exp_f32_e32 v0, v114
	v_exp_f32_e32 v177, v115
	v_exp_f32_e32 v179, v116
	v_exp_f32_e32 v254, v117
	v_add_f32_e32 v219, v0, v177
	v_cvt_pk_fp8_f32 v246, v0, v177
	v_add_f32_e32 v219, v179, v219
	v_add_f32_e32 v219, v254, v219
	v_cvt_pk_fp8_f32 v246, v179, v254 op_sel:[0,0,1]
	s_waitcnt lgkmcnt(2)
	v_mfma_scale_f32_32x32x64_f8f6f4 v[82:97], v[82:89], v[146:153], v[230:245], v194, v193 op_sel_hi:[0,0,0]
	v_exp_f32_e32 v0, v118
	v_exp_f32_e32 v177, v119
	v_exp_f32_e32 v179, v120
	v_exp_f32_e32 v254, v121
	v_add_f32_e32 v219, v0, v219
	v_add_f32_e32 v219, v177, v219
	v_cvt_pk_fp8_f32 v247, v0, v177
	v_add_f32_e32 v219, v179, v219
	v_add_f32_e32 v219, v254, v219
	v_cvt_pk_fp8_f32 v247, v179, v254 op_sel:[0,0,1]
	ds_read_b128 v[114:117], v213 offset:51200
	ds_read_b128 v[118:121], v214 offset:51200
	s_waitcnt lgkmcnt(2)
	v_mfma_scale_f32_32x32x64_f8f6f4 v[66:81], v[222:229], v[146:153], v[230:245], v194, v193 op_sel_hi:[0,0,0]
	ds_read_b128 v[222:225], v213 offset:55296
	ds_read_b128 v[226:229], v214 offset:55296
	v_exp_f32_e32 v0, v122
	v_exp_f32_e32 v177, v123
	v_exp_f32_e32 v179, v124
	v_exp_f32_e32 v254, v125
	v_add_f32_e32 v219, v0, v219
	v_add_f32_e32 v219, v177, v219
	v_cvt_pk_fp8_f32 v248, v0, v177
	v_add_f32_e32 v219, v179, v219
	v_add_f32_e32 v219, v254, v219
	v_cvt_pk_fp8_f32 v248, v179, v254 op_sel:[0,0,1]
	v_exp_f32_e32 v0, v126
	v_exp_f32_e32 v177, v127
	v_exp_f32_e32 v179, v128
	v_exp_f32_e32 v254, v129
	v_add_f32_e32 v219, v0, v219
	v_add_f32_e32 v219, v177, v219
	v_cvt_pk_fp8_f32 v249, v0, v177
	v_add_f32_e32 v219, v179, v219
	v_add_f32_e32 v219, v254, v219
	v_cvt_pk_fp8_f32 v249, v179, v254 op_sel:[0,0,1]
	ds_read_b128 v[122:125], v185 offset:59392
	ds_read_b128 v[126:129], v186 offset:59392
	s_waitcnt lgkmcnt(4)
	v_mfma_scale_f32_32x32x64_f8f6f4 v[82:97], v[114:121], v[138:145], v[82:97], v194, v193 op_sel_hi:[0,0,0]
	v_exp_f32_e32 v0, v98
	v_exp_f32_e32 v177, v99
	v_exp_f32_e32 v179, v100
	v_exp_f32_e32 v254, v101
	v_add_f32_e32 v219, v0, v219
	v_add_f32_e32 v219, v177, v219
	v_cvt_pk_fp8_f32 v250, v0, v177
	v_add_f32_e32 v219, v179, v219
	v_add_f32_e32 v219, v254, v219
	v_cvt_pk_fp8_f32 v250, v179, v254 op_sel:[0,0,1]
	s_waitcnt lgkmcnt(2)
	v_mfma_scale_f32_32x32x64_f8f6f4 v[66:81], v[222:229], v[138:145], v[66:81], v194, v193 op_sel_hi:[0,0,0]
	ds_read_b128 v[222:225], v185 offset:61440
	ds_read_b128 v[226:229], v186 offset:61440
	v_exp_f32_e32 v0, v102
	v_exp_f32_e32 v177, v103
	v_exp_f32_e32 v179, v104
	v_exp_f32_e32 v254, v105
	v_add_f32_e32 v219, v0, v219
	v_add_f32_e32 v219, v177, v219
	v_cvt_pk_fp8_f32 v251, v0, v177
	v_add_f32_e32 v219, v179, v219
	v_add_f32_e32 v219, v254, v219
	v_cvt_pk_fp8_f32 v251, v179, v254 op_sel:[0,0,1]
	v_exp_f32_e32 v0, v106
	v_exp_f32_e32 v177, v107
	v_exp_f32_e32 v179, v108
	v_exp_f32_e32 v254, v109
	v_add_f32_e32 v219, v0, v219
	v_add_f32_e32 v219, v177, v219
	v_cvt_pk_fp8_f32 v252, v0, v177
	v_add_f32_e32 v219, v179, v219
	v_add_f32_e32 v219, v254, v219
	v_cvt_pk_fp8_f32 v252, v179, v254 op_sel:[0,0,1]
	s_waitcnt lgkmcnt(2)
	v_mfma_scale_f32_32x32x64_f8f6f4 v[82:97], v[122:129], v[130:137], v[82:97], v194, v193 op_sel_hi:[0,0,0]
	v_exp_f32_e32 v0, v110
	v_exp_f32_e32 v177, v111
	v_exp_f32_e32 v179, v112
	v_exp_f32_e32 v254, v113
	v_add_f32_e32 v219, v0, v219
	v_add_f32_e32 v219, v177, v219
	v_cvt_pk_fp8_f32 v253, v0, v177
	v_add_f32_e32 v219, v179, v219
	v_add_f32_e32 v219, v254, v219
	v_cvt_pk_fp8_f32 v253, v179, v254 op_sel:[0,0,1]
	ds_read_b128 v[122:125], v185 offset:8192
	ds_read_b128 v[126:129], v186 offset:8192
	ds_read_b128 v[114:117], v185 offset:10240
	ds_read_b128 v[118:121], v186 offset:10240
	ds_read_b128 v[106:109], v185 offset:12288
	ds_read_b128 v[110:113], v186 offset:12288
	ds_read_b128 v[98:101], v185 offset:14336
	ds_read_b128 v[102:105], v186 offset:14336
	s_waitcnt lgkmcnt(8)
	v_mfma_scale_f32_32x32x64_f8f6f4 v[66:81], v[222:229], v[130:137], v[66:81], v194, v193 op_sel_hi:[0,0,0]
	v_mov_b32_e32 v0, v219
	s_nop 1
	v_permlane32_swap_b32_e32 v219, v0
	v_add_f32_e32 v219, v219, v0
	v_fma_f32 v209, v209, v221, v219
	v_max_f32_e32 v177, v82, v83
	v_max3_f32 v177, v177, v84, v85
	v_max3_f32 v177, v177, v86, v87
	v_max3_f32 v177, v177, v88, v89
	v_max3_f32 v177, v177, v90, v91
	v_max3_f32 v177, v177, v92, v93
	v_max3_f32 v177, v177, v94, v95
	v_max3_f32 v177, v177, v96, v97
	s_waitcnt lgkmcnt(6)
	v_mfma_scale_f32_32x32x64_f8f6f4 v[50:65], v[246:253], v[122:129], v[50:65], v194, v194 op_sel_hi:[0,0,0]
	s_waitcnt lgkmcnt(4)
	v_mfma_scale_f32_32x32x64_f8f6f4 v[34:49], v[246:253], v[114:121], v[34:49], v194, v194 op_sel_hi:[0,0,0]
	s_waitcnt vmcnt(0)
	ds_write_b128 v210, v[158:161]
	ds_write_b128 v211, v[162:165] offset:16384
	s_waitcnt lgkmcnt(4)
	v_mfma_scale_f32_32x32x64_f8f6f4 v[18:33], v[246:253], v[106:113], v[18:33], v194, v194 op_sel_hi:[0,0,0]
	s_waitcnt lgkmcnt(0)
	s_barrier
	global_load_dwordx4 v[158:161], v176, s[18:19]
	global_load_dwordx4 v[162:165], v178, s[16:17]
	v_add_u32_e32 v176, 0x2000, v176
	v_add_u32_e32 v178, 0x20000, v178
	s_waitcnt lgkmcnt(0)
	v_mfma_scale_f32_32x32x64_f8f6f4 v[2:17], v[246:253], v[98:105], v[2:17], v194, v194 op_sel_hi:[0,0,0]
	v_max_f32_e32 v0, v66, v67
	v_max3_f32 v0, v0, v68, v69
	v_max3_f32 v0, v0, v70, v71
	v_max3_f32 v0, v0, v72, v73
	v_max3_f32 v0, v0, v74, v75
	v_max3_f32 v0, v0, v76, v77
	v_max3_f32 v0, v0, v78, v79
	v_max3_f32 v0, v0, v80, v81
	v_max_f32_e32 v177, v177, v0
	v_mov_b32_e32 v0, v177
	v_mov_b32_e32 v218, 1.0
	s_nop 0
	v_permlane32_swap_b32_e32 v177, v0
	v_max_f32_e32 v177, v177, v0
	v_cmp_ge_f32_e32 vcc, s90, v177
	s_cmp_eq_u64 vcc, exec
	s_cbranch_scc0 .Lmla_s1_newmax
; __device__ __forceinline__ void finishSM9(f32x16& p0, f32x16& p1, float alpha, float& l_reg, v8i32& p8) {
; #pragma unroll
;   for (int r = 0; r < 16; ++r) { p0[r] = __builtin_amdgcn_exp2f(p0[r]); p1[r] = __builtin_amdgcn_exp2f(p1[r]); }
;   float ps = 0;
; #pragma unroll
;   for (int r = 0; r < 16; ++r) ps += p0[r];
; #pragma unroll
;   for (int r = 0; r < 16; ++r) ps += p1[r];
;   { auto rr = __builtin_amdgcn_permlane32_swap(__float_as_uint(ps), __float_as_uint(ps), false, false);
;     ps = __uint_as_float(rr[0]) + __uint_as_float(rr[1]); }
;   l_reg = l_reg * alpha + ps;
; #pragma unroll
;   for (int g = 0; g < 4; ++g) {
;     int w = __builtin_amdgcn_cvt_pk_fp8_f32(p0[4 * g], p0[4 * g + 1], 0, false); p8[g] = __builtin_amdgcn_cvt_pk_fp8_f32(p0[4 * g + 2], p0[4 * g + 3], w, true);
;     int u = __builtin_amdgcn_cvt_pk_fp8_f32(p1[4 * g], p1[4 * g + 1], 0, false); p8[4 + g] = __builtin_amdgcn_cvt_pk_fp8_f32(p1[4 * g + 2], p1[4 * g + 3], u, true); }
; }
; __device__ __forceinline__ void pv8(f32x16* o, const char* Vt, const v8i32 p8, int r32, int hi) {
;   const int sw = (r32 >> 2) & 3, a0 = r32 * 64 + (((hi * 2) ^ sw) << 4), a1 = r32 * 64 + (((hi * 2 + 1) ^ sw) << 4);
; #pragma unroll
;   for (int d0 = 0; d0 < 4; ++d0) {
;     const v8i32 vf = cat8(*reinterpret_cast<const v4i32*>(Vt + d0 * 2048 + a0), *reinterpret_cast<const v4i32*>(Vt + d0 * 2048 + a1));
;     o[d0] = __builtin_amdgcn_mfma_scale_f32_32x32x64_f8f6f4(p8, vf, o[d0], 0, 0, 0, 127, 0, 127); }
; }
; __device__ __forceinline__ void qkt9(f32x16& p0, f32x16& p1, const char* Kn, const char* Kr, const v8i32* qf, const float init, int r32, int hi) {
; #pragma unroll
;   for (int r = 0; r < 16; ++r) { p0[r] = init; p1[r] = init; }
; #pragma unroll
;   for (int s = 0; s < 2; ++s) { const int c0 = s * 4 + hi * 2;
;     const v8i32 a0 = cat8(*reinterpret_cast<const v4i32*>(Kn + KN8SW(r32, c0)), *reinterpret_cast<const v4i32*>(Kn + KN8SW(r32, c0 + 1)));
;     const v8i32 a1 = cat8(*reinterpret_cast<const v4i32*>(Kn + 4096 + KN8SW(r32, c0)), *reinterpret_cast<const v4i32*>(Kn + 4096 + KN8SW(r32, c0 + 1)));
;     p0 = __builtin_amdgcn_mfma_scale_f32_32x32x64_f8f6f4(a0, qf[s], p0, 0, 0, 0, 127, 0, 124);
;     p1 = __builtin_amdgcn_mfma_scale_f32_32x32x64_f8f6f4(a1, qf[s], p1, 0, 0, 0, 127, 0, 124); }
;   { const int c0 = hi * 2;
.Lmla_s1_cont:
	ds_read_b128 v[114:117], v215 offset:16384
	ds_read_b128 v[118:121], v216 offset:16384
	ds_read_b128 v[222:225], v215 offset:20480
	ds_read_b128 v[226:229], v216 offset:20480
	v_exp_f32_e32 v0, v82
	v_exp_f32_e32 v177, v83
	v_exp_f32_e32 v179, v84
	v_exp_f32_e32 v254, v85
	v_add_f32_e32 v219, v0, v177
	v_cvt_pk_fp8_f32 v246, v0, v177
	v_add_f32_e32 v219, v179, v219
	v_add_f32_e32 v219, v254, v219
	v_cvt_pk_fp8_f32 v246, v179, v254 op_sel:[0,0,1]
	s_waitcnt lgkmcnt(2)
	v_mfma_scale_f32_32x32x64_f8f6f4 v[114:129], v[114:121], v[146:153], v[230:245], v194, v193 op_sel_hi:[0,0,0]
	v_exp_f32_e32 v0, v86
	v_exp_f32_e32 v177, v87
	v_exp_f32_e32 v179, v88
	v_exp_f32_e32 v254, v89
	v_add_f32_e32 v219, v0, v219
	v_add_f32_e32 v219, v177, v219
	v_cvt_pk_fp8_f32 v247, v0, v177
	v_add_f32_e32 v219, v179, v219
	v_add_f32_e32 v219, v254, v219
	v_cvt_pk_fp8_f32 v247, v179, v254 op_sel:[0,0,1]
	ds_read_b128 v[82:85], v213 offset:16384
	ds_read_b128 v[86:89], v214 offset:16384
	s_waitcnt lgkmcnt(2)
	v_mfma_scale_f32_32x32x64_f8f6f4 v[98:113], v[222:229], v[146:153], v[230:245], v194, v193 op_sel_hi:[0,0,0]
	ds_read_b128 v[222:225], v213 offset:20480
	ds_read_b128 v[226:229], v214 offset:20480
	v_exp_f32_e32 v0, v90
	v_exp_f32_e32 v177, v91
	v_exp_f32_e32 v179, v92
	v_exp_f32_e32 v254, v93
	v_add_f32_e32 v219, v0, v219
	v_add_f32_e32 v219, v177, v219
	v_cvt_pk_fp8_f32 v248, v0, v177
	v_add_f32_e32 v219, v179, v219
	v_add_f32_e32 v219, v254, v219
	v_cvt_pk_fp8_f32 v248, v179, v254 op_sel:[0,0,1]
	v_exp_f32_e32 v0, v94
	v_exp_f32_e32 v177, v95
	v_exp_f32_e32 v179, v96
	v_exp_f32_e32 v254, v97
	v_add_f32_e32 v219, v0, v219
	v_add_f32_e32 v219, v177, v219
	v_cvt_pk_fp8_f32 v249, v0, v177
	v_add_f32_e32 v219, v179, v219
	v_add_f32_e32 v219, v254, v219
	v_cvt_pk_fp8_f32 v249, v179, v254 op_sel:[0,0,1]
	ds_read_b128 v[90:93], v185 offset:32768
	ds_read_b128 v[94:97], v186 offset:32768
	s_waitcnt lgkmcnt(4)
	v_mfma_scale_f32_32x32x64_f8f6f4 v[114:129], v[82:89], v[138:145], v[114:129], v194, v193 op_sel_hi:[0,0,0]
	v_exp_f32_e32 v0, v66
	v_exp_f32_e32 v177, v67
	v_exp_f32_e32 v179, v68
	v_exp_f32_e32 v254, v69
	v_add_f32_e32 v219, v0, v219
	v_add_f32_e32 v219, v177, v219
	v_cvt_pk_fp8_f32 v250, v0, v177
	v_add_f32_e32 v219, v179, v219
	v_add_f32_e32 v219, v254, v219
	v_cvt_pk_fp8_f32 v250, v179, v254 op_sel:[0,0,1]
	s_waitcnt lgkmcnt(2)
	v_mfma_scale_f32_32x32x64_f8f6f4 v[98:113], v[222:229], v[138:145], v[98:113], v194, v193 op_sel_hi:[0,0,0]
	ds_read_b128 v[222:225], v185 offset:34816
	ds_read_b128 v[226:229], v186 offset:34816
	v_exp_f32_e32 v0, v70
	v_exp_f32_e32 v177, v71
	v_exp_f32_e32 v179, v72
	v_exp_f32_e32 v254, v73
	v_add_f32_e32 v219, v0, v219
	v_add_f32_e32 v219, v177, v219
	v_cvt_pk_fp8_f32 v251, v0, v177
	v_add_f32_e32 v219, v179, v219
	v_add_f32_e32 v219, v254, v219
	v_cvt_pk_fp8_f32 v251, v179, v254 op_sel:[0,0,1]
	v_exp_f32_e32 v0, v74
	v_exp_f32_e32 v177, v75
	v_exp_f32_e32 v179, v76
	v_exp_f32_e32 v254, v77
	v_add_f32_e32 v219, v0, v219
	v_add_f32_e32 v219, v177, v219
	v_cvt_pk_fp8_f32 v252, v0, v177
	v_add_f32_e32 v219, v179, v219
	v_add_f32_e32 v219, v254, v219
	v_cvt_pk_fp8_f32 v252, v179, v254 op_sel:[0,0,1]
	s_waitcnt lgkmcnt(2)
	v_mfma_scale_f32_32x32x64_f8f6f4 v[114:129], v[90:97], v[130:137], v[114:129], v194, v193 op_sel_hi:[0,0,0]
	v_exp_f32_e32 v0, v78
	v_exp_f32_e32 v177, v79
	v_exp_f32_e32 v179, v80
	v_exp_f32_e32 v254, v81
	v_add_f32_e32 v219, v0, v219
	v_add_f32_e32 v219, v177, v219
	v_cvt_pk_fp8_f32 v253, v0, v177
	v_add_f32_e32 v219, v179, v219
	v_add_f32_e32 v219, v254, v219
	v_cvt_pk_fp8_f32 v253, v179, v254 op_sel:[0,0,1]
	ds_read_b128 v[90:93], v185 offset:43008
	ds_read_b128 v[94:97], v186 offset:43008
	ds_read_b128 v[82:85], v185 offset:45056
	ds_read_b128 v[86:89], v186 offset:45056
	ds_read_b128 v[74:77], v185 offset:47104
	ds_read_b128 v[78:81], v186 offset:47104
	ds_read_b128 v[66:69], v185 offset:49152
	ds_read_b128 v[70:73], v186 offset:49152
	s_waitcnt lgkmcnt(8)
	v_mfma_scale_f32_32x32x64_f8f6f4 v[98:113], v[222:229], v[130:137], v[98:113], v194, v193 op_sel_hi:[0,0,0]
	v_mov_b32_e32 v0, v219
	s_nop 1
	v_permlane32_swap_b32_e32 v219, v0
	v_add_f32_e32 v219, v219, v0
	v_fma_f32 v209, v209, v218, v219
	v_max_f32_e32 v177, v114, v115
	v_max3_f32 v177, v177, v116, v117
	v_max3_f32 v177, v177, v118, v119
	v_max3_f32 v177, v177, v120, v121
	v_max3_f32 v177, v177, v122, v123
	v_max3_f32 v177, v177, v124, v125
	v_max3_f32 v177, v177, v126, v127
	v_max3_f32 v177, v177, v128, v129
	s_waitcnt lgkmcnt(6)
	v_mfma_scale_f32_32x32x64_f8f6f4 v[50:65], v[246:253], v[90:97], v[50:65], v194, v194 op_sel_hi:[0,0,0]
	s_waitcnt lgkmcnt(4)
	v_mfma_scale_f32_32x32x64_f8f6f4 v[34:49], v[246:253], v[82:89], v[34:49], v194, v194 op_sel_hi:[0,0,0]
	s_waitcnt vmcnt(0)
	ds_write_b128 v210, v[158:161] offset:8192
	ds_write_b128 v211, v[162:165] offset:24576
	s_waitcnt lgkmcnt(4)
	v_mfma_scale_f32_32x32x64_f8f6f4 v[18:33], v[246:253], v[74:81], v[18:33], v194, v194 op_sel_hi:[0,0,0]
	s_waitcnt lgkmcnt(0)
	s_barrier
	global_load_dwordx4 v[158:161], v176, s[18:19]
	global_load_dwordx4 v[162:165], v178, s[16:17]
	v_add_u32_e32 v176, 0x2000, v176
	v_add_u32_e32 v178, 0x20000, v178
	s_waitcnt lgkmcnt(0)
	v_mfma_scale_f32_32x32x64_f8f6f4 v[2:17], v[246:253], v[66:73], v[2:17], v194, v194 op_sel_hi:[0,0,0]
	v_max_f32_e32 v0, v98, v99
	v_max3_f32 v0, v0, v100, v101
	v_max3_f32 v0, v0, v102, v103
	v_max3_f32 v0, v0, v104, v105
	v_max3_f32 v0, v0, v106, v107
	v_max3_f32 v0, v0, v108, v109
	v_max3_f32 v0, v0, v110, v111
	v_max3_f32 v0, v0, v112, v113
	v_max_f32_e32 v177, v177, v0
	v_mov_b32_e32 v0, v177
	v_mov_b32_e32 v221, 1.0
	s_nop 0
	v_permlane32_swap_b32_e32 v177, v0
	v_max_f32_e32 v177, v177, v0
	v_cmp_ge_f32_e32 vcc, s90, v177
	s_cmp_eq_u64 vcc, exec
	s_cbranch_scc0 .Lmla_s2_newmax
; __device__ __forceinline__ void finishSM9(f32x16& p0, f32x16& p1, float alpha, float& l_reg, v8i32& p8) {
; #pragma unroll
;   for (int r = 0; r < 16; ++r) { p0[r] = __builtin_amdgcn_exp2f(p0[r]); p1[r] = __builtin_amdgcn_exp2f(p1[r]); }
;   float ps = 0;
; #pragma unroll
;   for (int r = 0; r < 16; ++r) ps += p0[r];
; #pragma unroll
;   for (int r = 0; r < 16; ++r) ps += p1[r];
;   { auto rr = __builtin_amdgcn_permlane32_swap(__float_as_uint(ps), __float_as_uint(ps), false, false);
;     ps = __uint_as_float(rr[0]) + __uint_as_float(rr[1]); }
;   l_reg = l_reg * alpha + ps;
; #pragma unroll
;   for (int g = 0; g < 4; ++g) {
;     int w = __builtin_amdgcn_cvt_pk_fp8_f32(p0[4 * g], p0[4 * g + 1], 0, false); p8[g] = __builtin_amdgcn_cvt_pk_fp8_f32(p0[4 * g + 2], p0[4 * g + 3], w, true);
;     int u = __builtin_amdgcn_cvt_pk_fp8_f32(p1[4 * g], p1[4 * g + 1], 0, false); p8[4 + g] = __builtin_amdgcn_cvt_pk_fp8_f32(p1[4 * g + 2], p1[4 * g + 3], u, true); }
; }
; __device__ __forceinline__ void pv8(f32x16* o, const char* Vt, const v8i32 p8, int r32, int hi) {
;   const int sw = (r32 >> 2) & 3, a0 = r32 * 64 + (((hi * 2) ^ sw) << 4), a1 = r32 * 64 + (((hi * 2 + 1) ^ sw) << 4);
; #pragma unroll
;   for (int d0 = 0; d0 < 4; ++d0) {
;     const v8i32 vf = cat8(*reinterpret_cast<const v4i32*>(Vt + d0 * 2048 + a0), *reinterpret_cast<const v4i32*>(Vt + d0 * 2048 + a1));
;     o[d0] = __builtin_amdgcn_mfma_scale_f32_32x32x64_f8f6f4(p8, vf, o[d0], 0, 0, 0, 127, 0, 127); }
; }
; __device__ __forceinline__ void qkt9(f32x16& p0, f32x16& p1, const char* Kn, const char* Kr, const v8i32* qf, const float init, int r32, int hi) {
; #pragma unroll
;   for (int r = 0; r < 16; ++r) { p0[r] = init; p1[r] = init; }
; #pragma unroll
;   for (int s = 0; s < 2; ++s) { const int c0 = s * 4 + hi * 2;
;     const v8i32 a0 = cat8(*reinterpret_cast<const v4i32*>(Kn + KN8SW(r32, c0)), *reinterpret_cast<const v4i32*>(Kn + KN8SW(r32, c0 + 1)));
;     const v8i32 a1 = cat8(*reinterpret_cast<const v4i32*>(Kn + 4096 + KN8SW(r32, c0)), *reinterpret_cast<const v4i32*>(Kn + 4096 + KN8SW(r32, c0 + 1)));
;     p0 = __builtin_amdgcn_mfma_scale_f32_32x32x64_f8f6f4(a0, qf[s], p0, 0, 0, 0, 127, 0, 124);
;     p1 = __builtin_amdgcn_mfma_scale_f32_32x32x64_f8f6f4(a1, qf[s], p1, 0, 0, 0, 127, 0, 124); }
;   { const int c0 = hi * 2;
.Lmla_s2_cont:
	ds_read_b128 v[82:85], v215 offset:24576
	ds_read_b128 v[86:89], v216 offset:24576
	ds_read_b128 v[222:225], v215 offset:28672
	ds_read_b128 v[226:229], v216 offset:28672
	v_exp_f32_e32 v0, v114
	v_exp_f32_e32 v177, v115
	v_exp_f32_e32 v179, v116
	v_exp_f32_e32 v254, v117
	v_add_f32_e32 v219, v0, v177
	v_cvt_pk_fp8_f32 v246, v0, v177
	v_add_f32_e32 v219, v179, v219
	v_add_f32_e32 v219, v254, v219
	v_cvt_pk_fp8_f32 v246, v179, v254 op_sel:[0,0,1]
	s_waitcnt lgkmcnt(2)
	v_mfma_scale_f32_32x32x64_f8f6f4 v[82:97], v[82:89], v[146:153], v[230:245], v194, v193 op_sel_hi:[0,0,0]
	v_exp_f32_e32 v0, v118
	v_exp_f32_e32 v177, v119
	v_exp_f32_e32 v179, v120
	v_exp_f32_e32 v254, v121
	v_add_f32_e32 v219, v0, v219
	v_add_f32_e32 v219, v177, v219
	v_cvt_pk_fp8_f32 v247, v0, v177
	v_add_f32_e32 v219, v179, v219
	v_add_f32_e32 v219, v254, v219
	v_cvt_pk_fp8_f32 v247, v179, v254 op_sel:[0,0,1]
	ds_read_b128 v[114:117], v213 offset:24576
	ds_read_b128 v[118:121], v214 offset:24576
	s_waitcnt lgkmcnt(2)
	v_mfma_scale_f32_32x32x64_f8f6f4 v[66:81], v[222:229], v[146:153], v[230:245], v194, v193 op_sel_hi:[0,0,0]
	ds_read_b128 v[222:225], v213 offset:28672
	ds_read_b128 v[226:229], v214 offset:28672
	v_exp_f32_e32 v0, v122
	v_exp_f32_e32 v177, v123
	v_exp_f32_e32 v179, v124
	v_exp_f32_e32 v254, v125
	v_add_f32_e32 v219, v0, v219
	v_add_f32_e32 v219, v177, v219
	v_cvt_pk_fp8_f32 v248, v0, v177
	v_add_f32_e32 v219, v179, v219
	v_add_f32_e32 v219, v254, v219
	v_cvt_pk_fp8_f32 v248, v179, v254 op_sel:[0,0,1]
	v_exp_f32_e32 v0, v126
	v_exp_f32_e32 v177, v127
	v_exp_f32_e32 v179, v128
	v_exp_f32_e32 v254, v129
	v_add_f32_e32 v219, v0, v219
	v_add_f32_e32 v219, v177, v219
	v_cvt_pk_fp8_f32 v249, v0, v177
	v_add_f32_e32 v219, v179, v219
	v_add_f32_e32 v219, v254, v219
	v_cvt_pk_fp8_f32 v249, v179, v254 op_sel:[0,0,1]
	ds_read_b128 v[122:125], v185 offset:36864
	ds_read_b128 v[126:129], v186 offset:36864
	s_waitcnt lgkmcnt(4)
	v_mfma_scale_f32_32x32x64_f8f6f4 v[82:97], v[114:121], v[138:145], v[82:97], v194, v193 op_sel_hi:[0,0,0]
	v_exp_f32_e32 v0, v98
	v_exp_f32_e32 v177, v99
	v_exp_f32_e32 v179, v100
	v_exp_f32_e32 v254, v101
	v_add_f32_e32 v219, v0, v219
	v_add_f32_e32 v219, v177, v219
	v_cvt_pk_fp8_f32 v250, v0, v177
	v_add_f32_e32 v219, v179, v219
	v_add_f32_e32 v219, v254, v219
	v_cvt_pk_fp8_f32 v250, v179, v254 op_sel:[0,0,1]
	s_waitcnt lgkmcnt(2)
	v_mfma_scale_f32_32x32x64_f8f6f4 v[66:81], v[222:229], v[138:145], v[66:81], v194, v193 op_sel_hi:[0,0,0]
	ds_read_b128 v[222:225], v185 offset:38912
	ds_read_b128 v[226:229], v186 offset:38912
	v_exp_f32_e32 v0, v102
	v_exp_f32_e32 v177, v103
	v_exp_f32_e32 v179, v104
	v_exp_f32_e32 v254, v105
	v_add_f32_e32 v219, v0, v219
	v_add_f32_e32 v219, v177, v219
	v_cvt_pk_fp8_f32 v251, v0, v177
	v_add_f32_e32 v219, v179, v219
	v_add_f32_e32 v219, v254, v219
	v_cvt_pk_fp8_f32 v251, v179, v254 op_sel:[0,0,1]
	v_exp_f32_e32 v0, v106
	v_exp_f32_e32 v177, v107
	v_exp_f32_e32 v179, v108
	v_exp_f32_e32 v254, v109
	v_add_f32_e32 v219, v0, v219
	v_add_f32_e32 v219, v177, v219
	v_cvt_pk_fp8_f32 v252, v0, v177
	v_add_f32_e32 v219, v179, v219
	v_add_f32_e32 v219, v254, v219
	v_cvt_pk_fp8_f32 v252, v179, v254 op_sel:[0,0,1]
	s_waitcnt lgkmcnt(2)
	v_mfma_scale_f32_32x32x64_f8f6f4 v[82:97], v[122:129], v[130:137], v[82:97], v194, v193 op_sel_hi:[0,0,0]
	v_exp_f32_e32 v0, v110
	v_exp_f32_e32 v177, v111
	v_exp_f32_e32 v179, v112
	v_exp_f32_e32 v254, v113
	v_add_f32_e32 v219, v0, v219
	v_add_f32_e32 v219, v177, v219
	v_cvt_pk_fp8_f32 v253, v0, v177
	v_add_f32_e32 v219, v179, v219
	v_add_f32_e32 v219, v254, v219
	v_cvt_pk_fp8_f32 v253, v179, v254 op_sel:[0,0,1]
	ds_read_b128 v[122:125], v185 offset:0
	ds_read_b128 v[126:129], v186 offset:0
	ds_read_b128 v[114:117], v185 offset:2048
	ds_read_b128 v[118:121], v186 offset:2048
	ds_read_b128 v[106:109], v185 offset:4096
	ds_read_b128 v[110:113], v186 offset:4096
	ds_read_b128 v[98:101], v185 offset:6144
	ds_read_b128 v[102:105], v186 offset:6144
	s_waitcnt lgkmcnt(8)
	v_mfma_scale_f32_32x32x64_f8f6f4 v[66:81], v[222:229], v[130:137], v[66:81], v194, v193 op_sel_hi:[0,0,0]
	v_mov_b32_e32 v0, v219
	s_nop 1
	v_permlane32_swap_b32_e32 v219, v0
	v_add_f32_e32 v219, v219, v0
	v_fma_f32 v209, v209, v221, v219
	v_max_f32_e32 v177, v82, v83
	v_max3_f32 v177, v177, v84, v85
	v_max3_f32 v177, v177, v86, v87
	v_max3_f32 v177, v177, v88, v89
	v_max3_f32 v177, v177, v90, v91
	v_max3_f32 v177, v177, v92, v93
	v_max3_f32 v177, v177, v94, v95
	v_max3_f32 v177, v177, v96, v97
	s_waitcnt lgkmcnt(6)
	v_mfma_scale_f32_32x32x64_f8f6f4 v[50:65], v[246:253], v[122:129], v[50:65], v194, v194 op_sel_hi:[0,0,0]
	s_waitcnt lgkmcnt(4)
	v_mfma_scale_f32_32x32x64_f8f6f4 v[34:49], v[246:253], v[114:121], v[34:49], v194, v194 op_sel_hi:[0,0,0]
	s_waitcnt vmcnt(0)
	ds_write_b128 v210, v[158:161] offset:43008
	ds_write_b128 v211, v[162:165] offset:51200
	s_waitcnt lgkmcnt(4)
	v_mfma_scale_f32_32x32x64_f8f6f4 v[18:33], v[246:253], v[106:113], v[18:33], v194, v194 op_sel_hi:[0,0,0]
	s_waitcnt lgkmcnt(0)
	s_barrier
	global_load_dwordx4 v[158:161], v176, s[18:19]
	global_load_dwordx4 v[162:165], v178, s[16:17]
	v_add_u32_e32 v176, 0x2000, v176
	v_add_u32_e32 v178, 0x20000, v178
	s_waitcnt lgkmcnt(0)
	v_mfma_scale_f32_32x32x64_f8f6f4 v[2:17], v[246:253], v[98:105], v[2:17], v194, v194 op_sel_hi:[0,0,0]
	v_max_f32_e32 v0, v66, v67
	v_max3_f32 v0, v0, v68, v69
	v_max3_f32 v0, v0, v70, v71
	v_max3_f32 v0, v0, v72, v73
	v_max3_f32 v0, v0, v74, v75
	v_max3_f32 v0, v0, v76, v77
	v_max3_f32 v0, v0, v78, v79
	v_max3_f32 v0, v0, v80, v81
	v_max_f32_e32 v177, v177, v0
	v_mov_b32_e32 v0, v177
	v_mov_b32_e32 v218, 1.0
	s_nop 0
	v_permlane32_swap_b32_e32 v177, v0
	v_max_f32_e32 v177, v177, v0
	v_cmp_ge_f32_e32 vcc, s90, v177
	s_cmp_eq_u64 vcc, exec
	s_cbranch_scc0 .Lmla_s3_newmax
; __device__ __forceinline__ void finishSM9(f32x16& p0, f32x16& p1, float alpha, float& l_reg, v8i32& p8) {
; #pragma unroll
;   for (int r = 0; r < 16; ++r) { p0[r] = __builtin_amdgcn_exp2f(p0[r]); p1[r] = __builtin_amdgcn_exp2f(p1[r]); }
;   float ps = 0;
; #pragma unroll
;   for (int r = 0; r < 16; ++r) ps += p0[r];
; #pragma unroll
;   for (int r = 0; r < 16; ++r) ps += p1[r];
;   { auto rr = __builtin_amdgcn_permlane32_swap(__float_as_uint(ps), __float_as_uint(ps), false, false);
;     ps = __uint_as_float(rr[0]) + __uint_as_float(rr[1]); }
;   l_reg = l_reg * alpha + ps;
; #pragma unroll
;   for (int g = 0; g < 4; ++g) {
;     int w = __builtin_amdgcn_cvt_pk_fp8_f32(p0[4 * g], p0[4 * g + 1], 0, false); p8[g] = __builtin_amdgcn_cvt_pk_fp8_f32(p0[4 * g + 2], p0[4 * g + 3], w, true);
;     int u = __builtin_amdgcn_cvt_pk_fp8_f32(p1[4 * g], p1[4 * g + 1], 0, false); p8[4 + g] = __builtin_amdgcn_cvt_pk_fp8_f32(p1[4 * g + 2], p1[4 * g + 3], u, true); }
; }
; __device__ __forceinline__ void pv8(f32x16* o, const char* Vt, const v8i32 p8, int r32, int hi) {
;   const int sw = (r32 >> 2) & 3, a0 = r32 * 64 + (((hi * 2) ^ sw) << 4), a1 = r32 * 64 + (((hi * 2 + 1) ^ sw) << 4);
; #pragma unroll
;   for (int d0 = 0; d0 < 4; ++d0) {
;     const v8i32 vf = cat8(*reinterpret_cast<const v4i32*>(Vt + d0 * 2048 + a0), *reinterpret_cast<const v4i32*>(Vt + d0 * 2048 + a1));
;     o[d0] = __builtin_amdgcn_mfma_scale_f32_32x32x64_f8f6f4(p8, vf, o[d0], 0, 0, 0, 127, 0, 127); }
; }
; __device__ __forceinline__ void qkt9(f32x16& p0, f32x16& p1, const char* Kn, const char* Kr, const v8i32* qf, const float init, int r32, int hi) {
; #pragma unroll
;   for (int r = 0; r < 16; ++r) { p0[r] = init; p1[r] = init; }
; #pragma unroll
;   for (int s = 0; s < 2; ++s) { const int c0 = s * 4 + hi * 2;
;     const v8i32 a0 = cat8(*reinterpret_cast<const v4i32*>(Kn + KN8SW(r32, c0)), *reinterpret_cast<const v4i32*>(Kn + KN8SW(r32, c0 + 1)));
;     const v8i32 a1 = cat8(*reinterpret_cast<const v4i32*>(Kn + 4096 + KN8SW(r32, c0)), *reinterpret_cast<const v4i32*>(Kn + 4096 + KN8SW(r32, c0 + 1)));
;     p0 = __builtin_amdgcn_mfma_scale_f32_32x32x64_f8f6f4(a0, qf[s], p0, 0, 0, 0, 127, 0, 124);
;     p1 = __builtin_amdgcn_mfma_scale_f32_32x32x64_f8f6f4(a1, qf[s], p1, 0, 0, 0, 127, 0, 124); }
;   { const int c0 = hi * 2;
.Lmla_s3_cont:
	ds_read_b128 v[114:117], v215 offset:51200
	ds_read_b128 v[118:121], v216 offset:51200
	ds_read_b128 v[222:225], v215 offset:55296
	ds_read_b128 v[226:229], v216 offset:55296
	v_exp_f32_e32 v0, v82
	v_exp_f32_e32 v177, v83
	v_exp_f32_e32 v179, v84
	v_exp_f32_e32 v254, v85
	v_add_f32_e32 v219, v0, v177
	v_cvt_pk_fp8_f32 v246, v0, v177
	v_add_f32_e32 v219, v179, v219
	v_add_f32_e32 v219, v254, v219
	v_cvt_pk_fp8_f32 v246, v179, v254 op_sel:[0,0,1]
	s_waitcnt lgkmcnt(2)
	v_mfma_scale_f32_32x32x64_f8f6f4 v[114:129], v[114:121], v[146:153], v[230:245], v194, v193 op_sel_hi:[0,0,0]
	v_exp_f32_e32 v0, v86
	v_exp_f32_e32 v177, v87
	v_exp_f32_e32 v179, v88
	v_exp_f32_e32 v254, v89
	v_add_f32_e32 v219, v0, v219
	v_add_f32_e32 v219, v177, v219
	v_cvt_pk_fp8_f32 v247, v0, v177
	v_add_f32_e32 v219, v179, v219
	v_add_f32_e32 v219, v254, v219
	v_cvt_pk_fp8_f32 v247, v179, v254 op_sel:[0,0,1]
	ds_read_b128 v[82:85], v213 offset:51200
	ds_read_b128 v[86:89], v214 offset:51200
	s_waitcnt lgkmcnt(2)
	v_mfma_scale_f32_32x32x64_f8f6f4 v[98:113], v[222:229], v[146:153], v[230:245], v194, v193 op_sel_hi:[0,0,0]
	ds_read_b128 v[222:225], v213 offset:55296
	ds_read_b128 v[226:229], v214 offset:55296
	v_exp_f32_e32 v0, v90
	v_exp_f32_e32 v177, v91
	v_exp_f32_e32 v179, v92
	v_exp_f32_e32 v254, v93
	v_add_f32_e32 v219, v0, v219
	v_add_f32_e32 v219, v177, v219
	v_cvt_pk_fp8_f32 v248, v0, v177
	v_add_f32_e32 v219, v179, v219
	v_add_f32_e32 v219, v254, v219
	v_cvt_pk_fp8_f32 v248, v179, v254 op_sel:[0,0,1]
	v_exp_f32_e32 v0, v94
	v_exp_f32_e32 v177, v95
	v_exp_f32_e32 v179, v96
	v_exp_f32_e32 v254, v97
	v_add_f32_e32 v219, v0, v219
	v_add_f32_e32 v219, v177, v219
	v_cvt_pk_fp8_f32 v249, v0, v177
	v_add_f32_e32 v219, v179, v219
	v_add_f32_e32 v219, v254, v219
	v_cvt_pk_fp8_f32 v249, v179, v254 op_sel:[0,0,1]
	ds_read_b128 v[90:93], v185 offset:59392
	ds_read_b128 v[94:97], v186 offset:59392
	s_waitcnt lgkmcnt(4)
	v_mfma_scale_f32_32x32x64_f8f6f4 v[114:129], v[82:89], v[138:145], v[114:129], v194, v193 op_sel_hi:[0,0,0]
	v_exp_f32_e32 v0, v66
	v_exp_f32_e32 v177, v67
	v_exp_f32_e32 v179, v68
	v_exp_f32_e32 v254, v69
	v_add_f32_e32 v219, v0, v219
	v_add_f32_e32 v219, v177, v219
	v_cvt_pk_fp8_f32 v250, v0, v177
	v_add_f32_e32 v219, v179, v219
	v_add_f32_e32 v219, v254, v219
	v_cvt_pk_fp8_f32 v250, v179, v254 op_sel:[0,0,1]
	s_waitcnt lgkmcnt(2)
	v_mfma_scale_f32_32x32x64_f8f6f4 v[98:113], v[222:229], v[138:145], v[98:113], v194, v193 op_sel_hi:[0,0,0]
	ds_read_b128 v[222:225], v185 offset:61440
	ds_read_b128 v[226:229], v186 offset:61440
	v_exp_f32_e32 v0, v70
	v_exp_f32_e32 v177, v71
	v_exp_f32_e32 v179, v72
	v_exp_f32_e32 v254, v73
	v_add_f32_e32 v219, v0, v219
	v_add_f32_e32 v219, v177, v219
	v_cvt_pk_fp8_f32 v251, v0, v177
	v_add_f32_e32 v219, v179, v219
	v_add_f32_e32 v219, v254, v219
	v_cvt_pk_fp8_f32 v251, v179, v254 op_sel:[0,0,1]
	v_exp_f32_e32 v0, v74
	v_exp_f32_e32 v177, v75
	v_exp_f32_e32 v179, v76
	v_exp_f32_e32 v254, v77
	v_add_f32_e32 v219, v0, v219
	v_add_f32_e32 v219, v177, v219
	v_cvt_pk_fp8_f32 v252, v0, v177
	v_add_f32_e32 v219, v179, v219
	v_add_f32_e32 v219, v254, v219
	v_cvt_pk_fp8_f32 v252, v179, v254 op_sel:[0,0,1]
	s_waitcnt lgkmcnt(2)
	v_mfma_scale_f32_32x32x64_f8f6f4 v[114:129], v[90:97], v[130:137], v[114:129], v194, v193 op_sel_hi:[0,0,0]
	v_exp_f32_e32 v0, v78
	v_exp_f32_e32 v177, v79
	v_exp_f32_e32 v179, v80
	v_exp_f32_e32 v254, v81
	v_add_f32_e32 v219, v0, v219
	v_add_f32_e32 v219, v177, v219
	v_cvt_pk_fp8_f32 v253, v0, v177
	v_add_f32_e32 v219, v179, v219
	v_add_f32_e32 v219, v254, v219
	v_cvt_pk_fp8_f32 v253, v179, v254 op_sel:[0,0,1]
	ds_read_b128 v[90:93], v185 offset:8192
	ds_read_b128 v[94:97], v186 offset:8192
	ds_read_b128 v[82:85], v185 offset:10240
	ds_read_b128 v[86:89], v186 offset:10240
	ds_read_b128 v[74:77], v185 offset:12288
	ds_read_b128 v[78:81], v186 offset:12288
	ds_read_b128 v[66:69], v185 offset:14336
	ds_read_b128 v[70:73], v186 offset:14336
	s_waitcnt lgkmcnt(8)
	v_mfma_scale_f32_32x32x64_f8f6f4 v[98:113], v[222:229], v[130:137], v[98:113], v194, v193 op_sel_hi:[0,0,0]
	v_mov_b32_e32 v0, v219
	s_nop 1
	v_permlane32_swap_b32_e32 v219, v0
	v_add_f32_e32 v219, v219, v0
	v_fma_f32 v209, v209, v218, v219
	v_max_f32_e32 v177, v114, v115
	v_max3_f32 v177, v177, v116, v117
	v_max3_f32 v177, v177, v118, v119
	v_max3_f32 v177, v177, v120, v121
	v_max3_f32 v177, v177, v122, v123
	v_max3_f32 v177, v177, v124, v125
	v_max3_f32 v177, v177, v126, v127
	v_max3_f32 v177, v177, v128, v129
	s_waitcnt lgkmcnt(6)
	v_mfma_scale_f32_32x32x64_f8f6f4 v[50:65], v[246:253], v[90:97], v[50:65], v194, v194 op_sel_hi:[0,0,0]
	s_waitcnt lgkmcnt(4)
	v_mfma_scale_f32_32x32x64_f8f6f4 v[34:49], v[246:253], v[82:89], v[34:49], v194, v194 op_sel_hi:[0,0,0]
	s_waitcnt vmcnt(0)
	ds_write_b128 v210, v[158:161]
	ds_write_b128 v211, v[162:165] offset:16384
	s_waitcnt lgkmcnt(4)
	v_mfma_scale_f32_32x32x64_f8f6f4 v[18:33], v[246:253], v[74:81], v[18:33], v194, v194 op_sel_hi:[0,0,0]
	s_waitcnt lgkmcnt(0)
	s_barrier
	global_load_dwordx4 v[158:161], v176, s[18:19]
	global_load_dwordx4 v[162:165], v178, s[16:17]
	v_add_u32_e32 v176, 0x2000, v176
	v_add_u32_e32 v178, 0x20000, v178
	s_waitcnt lgkmcnt(0)
	v_mfma_scale_f32_32x32x64_f8f6f4 v[2:17], v[246:253], v[66:73], v[2:17], v194, v194 op_sel_hi:[0,0,0]
	v_max_f32_e32 v0, v98, v99
	v_max3_f32 v0, v0, v100, v101
	v_max3_f32 v0, v0, v102, v103
	v_max3_f32 v0, v0, v104, v105
	v_max3_f32 v0, v0, v106, v107
	v_max3_f32 v0, v0, v108, v109
	v_max3_f32 v0, v0, v110, v111
	v_max3_f32 v0, v0, v112, v113
	v_max_f32_e32 v177, v177, v0
	v_mov_b32_e32 v0, v177
	v_mov_b32_e32 v221, 1.0
	s_nop 0
	v_permlane32_swap_b32_e32 v177, v0
	v_max_f32_e32 v177, v177, v0
	v_cmp_ge_f32_e32 vcc, s90, v177
	s_cmp_eq_u64 vcc, exec
	s_cbranch_scc0 .Lmla_s4_newmax
; __device__ __forceinline__ void finishSM9(f32x16& p0, f32x16& p1, float alpha, float& l_reg, v8i32& p8) {
; #pragma unroll
;   for (int r = 0; r < 16; ++r) { p0[r] = __builtin_amdgcn_exp2f(p0[r]); p1[r] = __builtin_amdgcn_exp2f(p1[r]); }
;   float ps = 0;
; #pragma unroll
;   for (int r = 0; r < 16; ++r) ps += p0[r];
; #pragma unroll
;   for (int r = 0; r < 16; ++r) ps += p1[r];
;   { auto rr = __builtin_amdgcn_permlane32_swap(__float_as_uint(ps), __float_as_uint(ps), false, false);
;     ps = __uint_as_float(rr[0]) + __uint_as_float(rr[1]); }
;   l_reg = l_reg * alpha + ps;
; #pragma unroll
;   for (int g = 0; g < 4; ++g) {
;     int w = __builtin_amdgcn_cvt_pk_fp8_f32(p0[4 * g], p0[4 * g + 1], 0, false); p8[g] = __builtin_amdgcn_cvt_pk_fp8_f32(p0[4 * g + 2], p0[4 * g + 3], w, true);
;     int u = __builtin_amdgcn_cvt_pk_fp8_f32(p1[4 * g], p1[4 * g + 1], 0, false); p8[4 + g] = __builtin_amdgcn_cvt_pk_fp8_f32(p1[4 * g + 2], p1[4 * g + 3], u, true); }
; }
; __device__ __forceinline__ void pv8(f32x16* o, const char* Vt, const v8i32 p8, int r32, int hi) {
;   const int sw = (r32 >> 2) & 3, a0 = r32 * 64 + (((hi * 2) ^ sw) << 4), a1 = r32 * 64 + (((hi * 2 + 1) ^ sw) << 4);
; #pragma unroll
;   for (int d0 = 0; d0 < 4; ++d0) {
;     const v8i32 vf = cat8(*reinterpret_cast<const v4i32*>(Vt + d0 * 2048 + a0), *reinterpret_cast<const v4i32*>(Vt + d0 * 2048 + a1));
;     o[d0] = __builtin_amdgcn_mfma_scale_f32_32x32x64_f8f6f4(p8, vf, o[d0], 0, 0, 0, 127, 0, 127); }
; }
; __device__ __forceinline__ void qkt9(f32x16& p0, f32x16& p1, const char* Kn, const char* Kr, const v8i32* qf, const float init, int r32, int hi) {
; #pragma unroll
;   for (int r = 0; r < 16; ++r) { p0[r] = init; p1[r] = init; }
; #pragma unroll
;   for (int s = 0; s < 2; ++s) { const int c0 = s * 4 + hi * 2;
;     const v8i32 a0 = cat8(*reinterpret_cast<const v4i32*>(Kn + KN8SW(r32, c0)), *reinterpret_cast<const v4i32*>(Kn + KN8SW(r32, c0 + 1)));
;     const v8i32 a1 = cat8(*reinterpret_cast<const v4i32*>(Kn + 4096 + KN8SW(r32, c0)), *reinterpret_cast<const v4i32*>(Kn + 4096 + KN8SW(r32, c0 + 1)));
;     p0 = __builtin_amdgcn_mfma_scale_f32_32x32x64_f8f6f4(a0, qf[s], p0, 0, 0, 0, 127, 0, 124);
;     p1 = __builtin_amdgcn_mfma_scale_f32_32x32x64_f8f6f4(a1, qf[s], p1, 0, 0, 0, 127, 0, 124); }
;   { const int c0 = hi * 2;
.Lmla_s4_cont:
	ds_read_b128 v[82:85], v215 offset:16384
	ds_read_b128 v[86:89], v216 offset:16384
	ds_read_b128 v[222:225], v215 offset:20480
	ds_read_b128 v[226:229], v216 offset:20480
	v_exp_f32_e32 v0, v114
	v_exp_f32_e32 v177, v115
	v_exp_f32_e32 v179, v116
	v_exp_f32_e32 v254, v117
	v_add_f32_e32 v219, v0, v177
	v_cvt_pk_fp8_f32 v246, v0, v177
	v_add_f32_e32 v219, v179, v219
	v_add_f32_e32 v219, v254, v219
	v_cvt_pk_fp8_f32 v246, v179, v254 op_sel:[0,0,1]
	s_waitcnt lgkmcnt(2)
	v_mfma_scale_f32_32x32x64_f8f6f4 v[82:97], v[82:89], v[146:153], v[230:245], v194, v193 op_sel_hi:[0,0,0]
	v_exp_f32_e32 v0, v118
	v_exp_f32_e32 v177, v119
	v_exp_f32_e32 v179, v120
	v_exp_f32_e32 v254, v121
	v_add_f32_e32 v219, v0, v219
	v_add_f32_e32 v219, v177, v219
	v_cvt_pk_fp8_f32 v247, v0, v177
	v_add_f32_e32 v219, v179, v219
	v_add_f32_e32 v219, v254, v219
	v_cvt_pk_fp8_f32 v247, v179, v254 op_sel:[0,0,1]
	ds_read_b128 v[114:117], v213 offset:16384
	ds_read_b128 v[118:121], v214 offset:16384
	s_waitcnt lgkmcnt(2)
	v_mfma_scale_f32_32x32x64_f8f6f4 v[66:81], v[222:229], v[146:153], v[230:245], v194, v193 op_sel_hi:[0,0,0]
	ds_read_b128 v[222:225], v213 offset:20480
	ds_read_b128 v[226:229], v214 offset:20480
	v_exp_f32_e32 v0, v122
	v_exp_f32_e32 v177, v123
	v_exp_f32_e32 v179, v124
	v_exp_f32_e32 v254, v125
	v_add_f32_e32 v219, v0, v219
	v_add_f32_e32 v219, v177, v219
	v_cvt_pk_fp8_f32 v248, v0, v177
	v_add_f32_e32 v219, v179, v219
	v_add_f32_e32 v219, v254, v219
	v_cvt_pk_fp8_f32 v248, v179, v254 op_sel:[0,0,1]
	v_exp_f32_e32 v0, v126
	v_exp_f32_e32 v177, v127
	v_exp_f32_e32 v179, v128
	v_exp_f32_e32 v254, v129
	v_add_f32_e32 v219, v0, v219
	v_add_f32_e32 v219, v177, v219
	v_cvt_pk_fp8_f32 v249, v0, v177
	v_add_f32_e32 v219, v179, v219
	v_add_f32_e32 v219, v254, v219
	v_cvt_pk_fp8_f32 v249, v179, v254 op_sel:[0,0,1]
	ds_read_b128 v[122:125], v185 offset:32768
	ds_read_b128 v[126:129], v186 offset:32768
	s_waitcnt lgkmcnt(4)
	v_mfma_scale_f32_32x32x64_f8f6f4 v[82:97], v[114:121], v[138:145], v[82:97], v194, v193 op_sel_hi:[0,0,0]
	v_exp_f32_e32 v0, v98
	v_exp_f32_e32 v177, v99
	v_exp_f32_e32 v179, v100
	v_exp_f32_e32 v254, v101
	v_add_f32_e32 v219, v0, v219
	v_add_f32_e32 v219, v177, v219
	v_cvt_pk_fp8_f32 v250, v0, v177
	v_add_f32_e32 v219, v179, v219
	v_add_f32_e32 v219, v254, v219
	v_cvt_pk_fp8_f32 v250, v179, v254 op_sel:[0,0,1]
	s_waitcnt lgkmcnt(2)
	v_mfma_scale_f32_32x32x64_f8f6f4 v[66:81], v[222:229], v[138:145], v[66:81], v194, v193 op_sel_hi:[0,0,0]
	ds_read_b128 v[222:225], v185 offset:34816
	ds_read_b128 v[226:229], v186 offset:34816
	v_exp_f32_e32 v0, v102
	v_exp_f32_e32 v177, v103
	v_exp_f32_e32 v179, v104
	v_exp_f32_e32 v254, v105
	v_add_f32_e32 v219, v0, v219
	v_add_f32_e32 v219, v177, v219
	v_cvt_pk_fp8_f32 v251, v0, v177
	v_add_f32_e32 v219, v179, v219
	v_add_f32_e32 v219, v254, v219
	v_cvt_pk_fp8_f32 v251, v179, v254 op_sel:[0,0,1]
	v_exp_f32_e32 v0, v106
	v_exp_f32_e32 v177, v107
	v_exp_f32_e32 v179, v108
	v_exp_f32_e32 v254, v109
	v_add_f32_e32 v219, v0, v219
	v_add_f32_e32 v219, v177, v219
	v_cvt_pk_fp8_f32 v252, v0, v177
	v_add_f32_e32 v219, v179, v219
	v_add_f32_e32 v219, v254, v219
	v_cvt_pk_fp8_f32 v252, v179, v254 op_sel:[0,0,1]
	s_waitcnt lgkmcnt(2)
	v_mfma_scale_f32_32x32x64_f8f6f4 v[82:97], v[122:129], v[130:137], v[82:97], v194, v193 op_sel_hi:[0,0,0]
	v_exp_f32_e32 v0, v110
	v_exp_f32_e32 v177, v111
	v_exp_f32_e32 v179, v112
	v_exp_f32_e32 v254, v113
	v_add_f32_e32 v219, v0, v219
	v_add_f32_e32 v219, v177, v219
	v_cvt_pk_fp8_f32 v253, v0, v177
	v_add_f32_e32 v219, v179, v219
	v_add_f32_e32 v219, v254, v219
	v_cvt_pk_fp8_f32 v253, v179, v254 op_sel:[0,0,1]
	ds_read_b128 v[122:125], v185 offset:43008
	ds_read_b128 v[126:129], v186 offset:43008
	ds_read_b128 v[114:117], v185 offset:45056
	ds_read_b128 v[118:121], v186 offset:45056
	ds_read_b128 v[106:109], v185 offset:47104
	ds_read_b128 v[110:113], v186 offset:47104
	ds_read_b128 v[98:101], v185 offset:49152
	ds_read_b128 v[102:105], v186 offset:49152
	s_waitcnt lgkmcnt(8)
	v_mfma_scale_f32_32x32x64_f8f6f4 v[66:81], v[222:229], v[130:137], v[66:81], v194, v193 op_sel_hi:[0,0,0]
	v_mov_b32_e32 v0, v219
	s_nop 1
	v_permlane32_swap_b32_e32 v219, v0
	v_add_f32_e32 v219, v219, v0
	v_fma_f32 v209, v209, v221, v219
	v_max_f32_e32 v177, v82, v83
	v_max3_f32 v177, v177, v84, v85
	v_max3_f32 v177, v177, v86, v87
	v_max3_f32 v177, v177, v88, v89
	v_max3_f32 v177, v177, v90, v91
	v_max3_f32 v177, v177, v92, v93
	v_max3_f32 v177, v177, v94, v95
	v_max3_f32 v177, v177, v96, v97
	s_waitcnt lgkmcnt(6)
	v_mfma_scale_f32_32x32x64_f8f6f4 v[50:65], v[246:253], v[122:129], v[50:65], v194, v194 op_sel_hi:[0,0,0]
	s_waitcnt lgkmcnt(4)
	v_mfma_scale_f32_32x32x64_f8f6f4 v[34:49], v[246:253], v[114:121], v[34:49], v194, v194 op_sel_hi:[0,0,0]
	s_waitcnt vmcnt(0)
	ds_write_b128 v210, v[158:161] offset:8192
	ds_write_b128 v211, v[162:165] offset:24576
	s_waitcnt lgkmcnt(4)
	v_mfma_scale_f32_32x32x64_f8f6f4 v[18:33], v[246:253], v[106:113], v[18:33], v194, v194 op_sel_hi:[0,0,0]
	s_waitcnt lgkmcnt(0)
	s_barrier
	global_load_dwordx4 v[158:161], v176, s[18:19]
	global_load_dwordx4 v[162:165], v178, s[16:17]
	v_add_u32_e32 v176, 0x2000, v176
	v_add_u32_e32 v178, 0x20000, v178
	s_waitcnt lgkmcnt(0)
	v_mfma_scale_f32_32x32x64_f8f6f4 v[2:17], v[246:253], v[98:105], v[2:17], v194, v194 op_sel_hi:[0,0,0]
	v_max_f32_e32 v0, v66, v67
	v_max3_f32 v0, v0, v68, v69
	v_max3_f32 v0, v0, v70, v71
	v_max3_f32 v0, v0, v72, v73
	v_max3_f32 v0, v0, v74, v75
	v_max3_f32 v0, v0, v76, v77
	v_max3_f32 v0, v0, v78, v79
	v_max3_f32 v0, v0, v80, v81
	v_max_f32_e32 v177, v177, v0
	v_mov_b32_e32 v0, v177
	v_mov_b32_e32 v218, 1.0
	s_nop 0
	v_permlane32_swap_b32_e32 v177, v0
	v_max_f32_e32 v177, v177, v0
	v_cmp_ge_f32_e32 vcc, s90, v177
	s_cmp_eq_u64 vcc, exec
	s_cbranch_scc0 .Lmla_s5_newmax
; __device__ __forceinline__ void finishSM9(f32x16& p0, f32x16& p1, float alpha, float& l_reg, v8i32& p8) {
; #pragma unroll
;   for (int r = 0; r < 16; ++r) { p0[r] = __builtin_amdgcn_exp2f(p0[r]); p1[r] = __builtin_amdgcn_exp2f(p1[r]); }
;   float ps = 0;
; #pragma unroll
;   for (int r = 0; r < 16; ++r) ps += p0[r];
; #pragma unroll
;   for (int r = 0; r < 16; ++r) ps += p1[r];
;   { auto rr = __builtin_amdgcn_permlane32_swap(__float_as_uint(ps), __float_as_uint(ps), false, false);
;     ps = __uint_as_float(rr[0]) + __uint_as_float(rr[1]); }
;   l_reg = l_reg * alpha + ps;
; #pragma unroll
;   for (int g = 0; g < 4; ++g) {
;     int w = __builtin_amdgcn_cvt_pk_fp8_f32(p0[4 * g], p0[4 * g + 1], 0, false); p8[g] = __builtin_amdgcn_cvt_pk_fp8_f32(p0[4 * g + 2], p0[4 * g + 3], w, true);
;     int u = __builtin_amdgcn_cvt_pk_fp8_f32(p1[4 * g], p1[4 * g + 1], 0, false); p8[4 + g] = __builtin_amdgcn_cvt_pk_fp8_f32(p1[4 * g + 2], p1[4 * g + 3], u, true); }
; }
; __device__ __forceinline__ void pv8(f32x16* o, const char* Vt, const v8i32 p8, int r32, int hi) {
;   const int sw = (r32 >> 2) & 3, a0 = r32 * 64 + (((hi * 2) ^ sw) << 4), a1 = r32 * 64 + (((hi * 2 + 1) ^ sw) << 4);
; #pragma unroll
;   for (int d0 = 0; d0 < 4; ++d0) {
; __device__ __forceinline__ void attn_unit7(const unsigned char* __restrict__ Q8, int ldq, const unsigned char* __restrict__ Kn8, int ldk, const unsigned char* __restrict__ Kr8, ...
;     ...
;   for (int j = 1; j + 1 < NT; j += 2) {
;     SLOAD();
;     qkt9(pB0, pB1, Kn_lds + 8192, Kr_lds + 4096, qf, 7.0f - m_reg, r32, hi);
;     finishSM9(pA0, pA1, alA, l_reg, p8);
;     pv8(o, Vt_lds, p8, r32, hi); partialSM9(pB0, pB1, m_reg, alB, thr_raw);
;     __syncthreads(); SWRITE(0);
;     RESC(alB); __syncthreads();
;     if (j + 2 < NT) SLOAD();
;     qkt9(pA0, pA1, Kn_lds, Kr_lds, qf, 7.0f - m_reg, r32, hi);
;     finishSM9(pB0, pB1, alB, l_reg, p8);
;     pv8(o, Vt_lds + 8192, p8, r32, hi); partialSM9(pA0, pA1, m_reg, alA, thr_raw);
;     __syncthreads(); if (j + 2 < NT) SWRITE(1);
;     RESC(alA); __syncthreads();
;   }
;   qkt9(pB0, pB1, Kn_lds + 8192, Kr_lds + 4096, qf, 7.0f - m_reg, r32, hi);
;   finishSM9(pA0, pA1, alA, l_reg, p8);
;   pv8(o, Vt_lds, p8, r32, hi); partialSM9(pB0, pB1, m_reg, alB, thr_raw);
;   RESC(alB);
;   finishSM9(pB0, pB1, alB, l_reg, p8);
;   pv8(o, Vt_lds + 8192, p8, r32, hi);
.Lmla_s5_cont:
	s_add_i32 s30, s30, 1
	s_cmpk_lt_u32 s30, 42
	s_cbranch_scc1 .Lmla_stag_loop
	ds_read_b128 v[114:117], v215 offset:24576
	ds_read_b128 v[118:121], v216 offset:24576
	ds_read_b128 v[222:225], v215 offset:28672
	ds_read_b128 v[226:229], v216 offset:28672
	v_exp_f32_e32 v0, v82
	v_exp_f32_e32 v177, v83
	v_exp_f32_e32 v179, v84
	v_exp_f32_e32 v254, v85
	v_add_f32_e32 v219, v0, v177
	v_cvt_pk_fp8_f32 v246, v0, v177
	v_add_f32_e32 v219, v179, v219
	v_add_f32_e32 v219, v254, v219
	v_cvt_pk_fp8_f32 v246, v179, v254 op_sel:[0,0,1]
	s_waitcnt lgkmcnt(2)
	v_mfma_scale_f32_32x32x64_f8f6f4 v[114:129], v[114:121], v[146:153], v[230:245], v194, v193 op_sel_hi:[0,0,0]
	v_exp_f32_e32 v0, v86
	v_exp_f32_e32 v177, v87
	v_exp_f32_e32 v179, v88
	v_exp_f32_e32 v254, v89
	v_add_f32_e32 v219, v0, v219
	v_add_f32_e32 v219, v177, v219
	v_cvt_pk_fp8_f32 v247, v0, v177
	v_add_f32_e32 v219, v179, v219
	v_add_f32_e32 v219, v254, v219
	v_cvt_pk_fp8_f32 v247, v179, v254 op_sel:[0,0,1]
	ds_read_b128 v[82:85], v213 offset:24576
	ds_read_b128 v[86:89], v214 offset:24576
	s_waitcnt lgkmcnt(2)
	v_mfma_scale_f32_32x32x64_f8f6f4 v[98:113], v[222:229], v[146:153], v[230:245], v194, v193 op_sel_hi:[0,0,0]
	ds_read_b128 v[222:225], v213 offset:28672
	ds_read_b128 v[226:229], v214 offset:28672
	v_exp_f32_e32 v0, v90
	v_exp_f32_e32 v177, v91
	v_exp_f32_e32 v179, v92
	v_exp_f32_e32 v254, v93
	v_add_f32_e32 v219, v0, v219
	v_add_f32_e32 v219, v177, v219
	v_cvt_pk_fp8_f32 v248, v0, v177
	v_add_f32_e32 v219, v179, v219
	v_add_f32_e32 v219, v254, v219
	v_cvt_pk_fp8_f32 v248, v179, v254 op_sel:[0,0,1]
	v_exp_f32_e32 v0, v94
	v_exp_f32_e32 v177, v95
	v_exp_f32_e32 v179, v96
	v_exp_f32_e32 v254, v97
	v_add_f32_e32 v219, v0, v219
	v_add_f32_e32 v219, v177, v219
	v_cvt_pk_fp8_f32 v249, v0, v177
	v_add_f32_e32 v219, v179, v219
	v_add_f32_e32 v219, v254, v219
	v_cvt_pk_fp8_f32 v249, v179, v254 op_sel:[0,0,1]
	ds_read_b128 v[90:93], v185 offset:36864
	ds_read_b128 v[94:97], v186 offset:36864
	s_waitcnt lgkmcnt(4)
	v_mfma_scale_f32_32x32x64_f8f6f4 v[114:129], v[82:89], v[138:145], v[114:129], v194, v193 op_sel_hi:[0,0,0]
	v_exp_f32_e32 v0, v66
	v_exp_f32_e32 v177, v67
	v_exp_f32_e32 v179, v68
	v_exp_f32_e32 v254, v69
	v_add_f32_e32 v219, v0, v219
	v_add_f32_e32 v219, v177, v219
	v_cvt_pk_fp8_f32 v250, v0, v177
	v_add_f32_e32 v219, v179, v219
	v_add_f32_e32 v219, v254, v219
	v_cvt_pk_fp8_f32 v250, v179, v254 op_sel:[0,0,1]
	s_waitcnt lgkmcnt(2)
	v_mfma_scale_f32_32x32x64_f8f6f4 v[98:113], v[222:229], v[138:145], v[98:113], v194, v193 op_sel_hi:[0,0,0]
	ds_read_b128 v[222:225], v185 offset:38912
	ds_read_b128 v[226:229], v186 offset:38912
	v_exp_f32_e32 v0, v70
	v_exp_f32_e32 v177, v71
	v_exp_f32_e32 v179, v72
	v_exp_f32_e32 v254, v73
	v_add_f32_e32 v219, v0, v219
	v_add_f32_e32 v219, v177, v219
	v_cvt_pk_fp8_f32 v251, v0, v177
	v_add_f32_e32 v219, v179, v219
	v_add_f32_e32 v219, v254, v219
	v_cvt_pk_fp8_f32 v251, v179, v254 op_sel:[0,0,1]
	v_exp_f32_e32 v0, v74
	v_exp_f32_e32 v177, v75
	v_exp_f32_e32 v179, v76
	v_exp_f32_e32 v254, v77
	v_add_f32_e32 v219, v0, v219
	v_add_f32_e32 v219, v177, v219
	v_cvt_pk_fp8_f32 v252, v0, v177
	v_add_f32_e32 v219, v179, v219
	v_add_f32_e32 v219, v254, v219
	v_cvt_pk_fp8_f32 v252, v179, v254 op_sel:[0,0,1]
	s_waitcnt lgkmcnt(2)
	v_mfma_scale_f32_32x32x64_f8f6f4 v[114:129], v[90:97], v[130:137], v[114:129], v194, v193 op_sel_hi:[0,0,0]
	v_exp_f32_e32 v0, v78
	v_exp_f32_e32 v177, v79
	v_exp_f32_e32 v179, v80
	v_exp_f32_e32 v254, v81
	v_add_f32_e32 v219, v0, v219
	v_add_f32_e32 v219, v177, v219
	v_cvt_pk_fp8_f32 v253, v0, v177
	v_add_f32_e32 v219, v179, v219
	v_add_f32_e32 v219, v254, v219
	v_cvt_pk_fp8_f32 v253, v179, v254 op_sel:[0,0,1]
	ds_read_b128 v[90:93], v185 offset:0
	ds_read_b128 v[94:97], v186 offset:0
	ds_read_b128 v[82:85], v185 offset:2048
	ds_read_b128 v[86:89], v186 offset:2048
	ds_read_b128 v[74:77], v185 offset:4096
	ds_read_b128 v[78:81], v186 offset:4096
	ds_read_b128 v[66:69], v185 offset:6144
	ds_read_b128 v[70:73], v186 offset:6144
	s_waitcnt lgkmcnt(8)
	v_mfma_scale_f32_32x32x64_f8f6f4 v[98:113], v[222:229], v[130:137], v[98:113], v194, v193 op_sel_hi:[0,0,0]
	v_mov_b32_e32 v0, v219
	s_nop 1
	v_permlane32_swap_b32_e32 v219, v0
	v_add_f32_e32 v219, v219, v0
	v_fma_f32 v209, v209, v218, v219
	v_max_f32_e32 v177, v114, v115
	v_max3_f32 v177, v177, v116, v117
	v_max3_f32 v177, v177, v118, v119
	v_max3_f32 v177, v177, v120, v121
	v_max3_f32 v177, v177, v122, v123
	v_max3_f32 v177, v177, v124, v125
	v_max3_f32 v177, v177, v126, v127
	v_max3_f32 v177, v177, v128, v129
	s_waitcnt lgkmcnt(6)
	v_mfma_scale_f32_32x32x64_f8f6f4 v[50:65], v[246:253], v[90:97], v[50:65], v194, v194 op_sel_hi:[0,0,0]
	s_waitcnt lgkmcnt(4)
	v_mfma_scale_f32_32x32x64_f8f6f4 v[34:49], v[246:253], v[82:89], v[34:49], v194, v194 op_sel_hi:[0,0,0]
	s_waitcnt vmcnt(0)
	ds_write_b128 v210, v[158:161] offset:43008
	ds_write_b128 v211, v[162:165] offset:51200
	s_waitcnt lgkmcnt(4)
	v_mfma_scale_f32_32x32x64_f8f6f4 v[18:33], v[246:253], v[74:81], v[18:33], v194, v194 op_sel_hi:[0,0,0]
	s_waitcnt lgkmcnt(0)
	s_barrier
	global_load_dwordx4 v[158:161], v176, s[18:19]
	global_load_dwordx4 v[162:165], v178, s[16:17]
	v_add_u32_e32 v176, 0x2000, v176
	v_add_u32_e32 v178, 0x20000, v178
	s_waitcnt lgkmcnt(0)
	v_mfma_scale_f32_32x32x64_f8f6f4 v[2:17], v[246:253], v[66:73], v[2:17], v194, v194 op_sel_hi:[0,0,0]
	v_max_f32_e32 v0, v98, v99
	v_max3_f32 v0, v0, v100, v101
	v_max3_f32 v0, v0, v102, v103
	v_max3_f32 v0, v0, v104, v105
	v_max3_f32 v0, v0, v106, v107
	v_max3_f32 v0, v0, v108, v109
	v_max3_f32 v0, v0, v110, v111
	v_max3_f32 v0, v0, v112, v113
	v_max_f32_e32 v177, v177, v0
	v_mov_b32_e32 v0, v177
	v_mov_b32_e32 v221, 1.0
	s_nop 0
	v_permlane32_swap_b32_e32 v177, v0
	v_max_f32_e32 v177, v177, v0
	v_cmp_ge_f32_e32 vcc, s90, v177
	s_cmp_eq_u64 vcc, exec
	s_cbranch_scc0 .Lmla_q0_newmax
; __device__ __forceinline__ v8i32 cat8(v4i32 a, v4i32 b) { return (v8i32){a[0], a[1], a[2], a[3], b[0], b[1], b[2], b[3]}; }
; __device__ __forceinline__ void finishSM9(f32x16& p0, f32x16& p1, float alpha, float& l_reg, v8i32& p8) {
; #pragma unroll
;   for (int r = 0; r < 16; ++r) { p0[r] = __builtin_amdgcn_exp2f(p0[r]); p1[r] = __builtin_amdgcn_exp2f(p1[r]); }
;   float ps = 0;
; #pragma unroll
;   for (int r = 0; r < 16; ++r) ps += p0[r];
; #pragma unroll
;   for (int r = 0; r < 16; ++r) ps += p1[r];
;   { auto rr = __builtin_amdgcn_permlane32_swap(__float_as_uint(ps), __float_as_uint(ps), false, false);
;     ps = __uint_as_float(rr[0]) + __uint_as_float(rr[1]); }
;   l_reg = l_reg * alpha + ps;
; #pragma unroll
;   for (int g = 0; g < 4; ++g) {
;     int w = __builtin_amdgcn_cvt_pk_fp8_f32(p0[4 * g], p0[4 * g + 1], 0, false); p8[g] = __builtin_amdgcn_cvt_pk_fp8_f32(p0[4 * g + 2], p0[4 * g + 3], w, true);
;     int u = __builtin_amdgcn_cvt_pk_fp8_f32(p1[4 * g], p1[4 * g + 1], 0, false); p8[4 + g] = __builtin_amdgcn_cvt_pk_fp8_f32(p1[4 * g + 2], p1[4 * g + 3], u, true); }
; }
; __device__ __forceinline__ void pv8(f32x16* o, const char* Vt, const v8i32 p8, int r32, int hi) {
;   const int sw = (r32 >> 2) & 3, a0 = r32 * 64 + (((hi * 2) ^ sw) << 4), a1 = r32 * 64 + (((hi * 2 + 1) ^ sw) << 4);
; #pragma unroll
;   for (int d0 = 0; d0 < 4; ++d0) {
;     const v8i32 vf = cat8(*reinterpret_cast<const v4i32*>(Vt + d0 * 2048 + a0), *reinterpret_cast<const v4i32*>(Vt + d0 * 2048 + a1));
;     o[d0] = __builtin_amdgcn_mfma_scale_f32_32x32x64_f8f6f4(p8, vf, o[d0], 0, 0, 0, 127, 0, 127); }
; }
; __device__ __forceinline__ void qkt9(f32x16& p0, f32x16& p1, const char* Kn, const char* Kr, const v8i32* qf, const float init, int r32, int hi) {
; #pragma unroll
;   for (int r = 0; r < 16; ++r) { p0[r] = init; p1[r] = init; }
; #pragma unroll
;   for (int s = 0; s < 2; ++s) { const int c0 = s * 4 + hi * 2;
; __device__ __forceinline__ void attn_unit7(const unsigned char* __restrict__ Q8, int ldq, const unsigned char* __restrict__ Kn8, int ldk, const unsigned char* __restrict__ Kr8, ...
;     ...
;   qkt9(pB0, pB1, Kn_lds + 8192, Kr_lds + 4096, qf, 7.0f - m_reg, r32, hi);
;   finishSM9(pA0, pA1, alA, l_reg, p8);
;   pv8(o, Vt_lds, p8, r32, hi); partialSM9(pB0, pB1, m_reg, alB, thr_raw);
;   RESC(alB);
;   finishSM9(pB0, pB1, alB, l_reg, p8);
;   pv8(o, Vt_lds + 8192, p8, r32, hi);
.Lmla_q0_cont:
	ds_read_b128 v[82:85], v215 offset:51200
	ds_read_b128 v[86:89], v216 offset:51200
	ds_read_b128 v[222:225], v215 offset:55296
	ds_read_b128 v[226:229], v216 offset:55296
	v_exp_f32_e32 v0, v114
	v_exp_f32_e32 v177, v115
	v_exp_f32_e32 v179, v116
	v_exp_f32_e32 v254, v117
	v_add_f32_e32 v219, v0, v177
	v_cvt_pk_fp8_f32 v246, v0, v177
	v_add_f32_e32 v219, v179, v219
	v_add_f32_e32 v219, v254, v219
	v_cvt_pk_fp8_f32 v246, v179, v254 op_sel:[0,0,1]
	s_waitcnt lgkmcnt(2)
	v_mfma_scale_f32_32x32x64_f8f6f4 v[82:97], v[82:89], v[146:153], v[230:245], v194, v193 op_sel_hi:[0,0,0]
	v_exp_f32_e32 v0, v118
	v_exp_f32_e32 v177, v119
	v_exp_f32_e32 v179, v120
	v_exp_f32_e32 v254, v121
	v_add_f32_e32 v219, v0, v219
	v_add_f32_e32 v219, v177, v219
	v_cvt_pk_fp8_f32 v247, v0, v177
	v_add_f32_e32 v219, v179, v219
	v_add_f32_e32 v219, v254, v219
	v_cvt_pk_fp8_f32 v247, v179, v254 op_sel:[0,0,1]
	ds_read_b128 v[114:117], v213 offset:51200
	ds_read_b128 v[118:121], v214 offset:51200
	s_waitcnt lgkmcnt(2)
	v_mfma_scale_f32_32x32x64_f8f6f4 v[66:81], v[222:229], v[146:153], v[230:245], v194, v193 op_sel_hi:[0,0,0]
	ds_read_b128 v[222:225], v213 offset:55296
	ds_read_b128 v[226:229], v214 offset:55296
	v_exp_f32_e32 v0, v122
	v_exp_f32_e32 v177, v123
	v_exp_f32_e32 v179, v124
	v_exp_f32_e32 v254, v125
	v_add_f32_e32 v219, v0, v219
	v_add_f32_e32 v219, v177, v219
	v_cvt_pk_fp8_f32 v248, v0, v177
	v_add_f32_e32 v219, v179, v219
	v_add_f32_e32 v219, v254, v219
	v_cvt_pk_fp8_f32 v248, v179, v254 op_sel:[0,0,1]
	v_exp_f32_e32 v0, v126
	v_exp_f32_e32 v177, v127
	v_exp_f32_e32 v179, v128
	v_exp_f32_e32 v254, v129
	v_add_f32_e32 v219, v0, v219
	v_add_f32_e32 v219, v177, v219
	v_cvt_pk_fp8_f32 v249, v0, v177
	v_add_f32_e32 v219, v179, v219
	v_add_f32_e32 v219, v254, v219
	v_cvt_pk_fp8_f32 v249, v179, v254 op_sel:[0,0,1]
	ds_read_b128 v[122:125], v185 offset:59392
	ds_read_b128 v[126:129], v186 offset:59392
	s_waitcnt lgkmcnt(4)
	v_mfma_scale_f32_32x32x64_f8f6f4 v[82:97], v[114:121], v[138:145], v[82:97], v194, v193 op_sel_hi:[0,0,0]
	v_exp_f32_e32 v0, v98
	v_exp_f32_e32 v177, v99
	v_exp_f32_e32 v179, v100
	v_exp_f32_e32 v254, v101
	v_add_f32_e32 v219, v0, v219
	v_add_f32_e32 v219, v177, v219
	v_cvt_pk_fp8_f32 v250, v0, v177
	v_add_f32_e32 v219, v179, v219
	v_add_f32_e32 v219, v254, v219
	v_cvt_pk_fp8_f32 v250, v179, v254 op_sel:[0,0,1]
	s_waitcnt lgkmcnt(2)
	v_mfma_scale_f32_32x32x64_f8f6f4 v[66:81], v[222:229], v[138:145], v[66:81], v194, v193 op_sel_hi:[0,0,0]
	ds_read_b128 v[222:225], v185 offset:61440
	ds_read_b128 v[226:229], v186 offset:61440
	v_exp_f32_e32 v0, v102
	v_exp_f32_e32 v177, v103
	v_exp_f32_e32 v179, v104
	v_exp_f32_e32 v254, v105
	v_add_f32_e32 v219, v0, v219
	v_add_f32_e32 v219, v177, v219
	v_cvt_pk_fp8_f32 v251, v0, v177
	v_add_f32_e32 v219, v179, v219
	v_add_f32_e32 v219, v254, v219
	v_cvt_pk_fp8_f32 v251, v179, v254 op_sel:[0,0,1]
	v_exp_f32_e32 v0, v106
	v_exp_f32_e32 v177, v107
	v_exp_f32_e32 v179, v108
	v_exp_f32_e32 v254, v109
	v_add_f32_e32 v219, v0, v219
	v_add_f32_e32 v219, v177, v219
	v_cvt_pk_fp8_f32 v252, v0, v177
	v_add_f32_e32 v219, v179, v219
	v_add_f32_e32 v219, v254, v219
	v_cvt_pk_fp8_f32 v252, v179, v254 op_sel:[0,0,1]
	s_waitcnt lgkmcnt(2)
	v_mfma_scale_f32_32x32x64_f8f6f4 v[82:97], v[122:129], v[130:137], v[82:97], v194, v193 op_sel_hi:[0,0,0]
	v_exp_f32_e32 v0, v110
	v_exp_f32_e32 v177, v111
	v_exp_f32_e32 v179, v112
	v_exp_f32_e32 v254, v113
	v_add_f32_e32 v219, v0, v219
	v_add_f32_e32 v219, v177, v219
	v_cvt_pk_fp8_f32 v253, v0, v177
	v_add_f32_e32 v219, v179, v219
	v_add_f32_e32 v219, v254, v219
	v_cvt_pk_fp8_f32 v253, v179, v254 op_sel:[0,0,1]
	ds_read_b128 v[122:125], v185 offset:8192
	ds_read_b128 v[126:129], v186 offset:8192
	ds_read_b128 v[114:117], v185 offset:10240
	ds_read_b128 v[118:121], v186 offset:10240
	ds_read_b128 v[106:109], v185 offset:12288
	ds_read_b128 v[110:113], v186 offset:12288
	ds_read_b128 v[98:101], v185 offset:14336
	ds_read_b128 v[102:105], v186 offset:14336
	s_waitcnt lgkmcnt(8)
	v_mfma_scale_f32_32x32x64_f8f6f4 v[66:81], v[222:229], v[130:137], v[66:81], v194, v193 op_sel_hi:[0,0,0]
	v_mov_b32_e32 v0, v219
	s_nop 1
	v_permlane32_swap_b32_e32 v219, v0
	v_add_f32_e32 v219, v219, v0
	v_fma_f32 v209, v209, v221, v219
	v_max_f32_e32 v177, v82, v83
	v_max3_f32 v177, v177, v84, v85
	v_max3_f32 v177, v177, v86, v87
	v_max3_f32 v177, v177, v88, v89
	v_max3_f32 v177, v177, v90, v91
	v_max3_f32 v177, v177, v92, v93
	v_max3_f32 v177, v177, v94, v95
	v_max3_f32 v177, v177, v96, v97
	s_waitcnt lgkmcnt(6)
	v_mfma_scale_f32_32x32x64_f8f6f4 v[50:65], v[246:253], v[122:129], v[50:65], v194, v194 op_sel_hi:[0,0,0]
	s_waitcnt lgkmcnt(4)
	v_mfma_scale_f32_32x32x64_f8f6f4 v[34:49], v[246:253], v[114:121], v[34:49], v194, v194 op_sel_hi:[0,0,0]
	s_waitcnt vmcnt(0)
	ds_write_b128 v210, v[158:161]
	ds_write_b128 v211, v[162:165] offset:16384
	s_waitcnt lgkmcnt(4)
	v_mfma_scale_f32_32x32x64_f8f6f4 v[18:33], v[246:253], v[106:113], v[18:33], v194, v194 op_sel_hi:[0,0,0]
	s_waitcnt lgkmcnt(0)
	s_barrier
	s_waitcnt lgkmcnt(0)
	v_mfma_scale_f32_32x32x64_f8f6f4 v[2:17], v[246:253], v[98:105], v[2:17], v194, v194 op_sel_hi:[0,0,0]
	v_max_f32_e32 v0, v66, v67
	v_max3_f32 v0, v0, v68, v69
	v_max3_f32 v0, v0, v70, v71
	v_max3_f32 v0, v0, v72, v73
	v_max3_f32 v0, v0, v74, v75
	v_max3_f32 v0, v0, v76, v77
	v_max3_f32 v0, v0, v78, v79
	v_max3_f32 v0, v0, v80, v81
	v_max_f32_e32 v177, v177, v0
	v_mov_b32_e32 v0, v177
	v_mov_b32_e32 v218, 1.0
	s_nop 0
	v_permlane32_swap_b32_e32 v177, v0
	v_max_f32_e32 v177, v177, v0
	v_cmp_ge_f32_e32 vcc, s90, v177
	s_cmp_eq_u64 vcc, exec
	s_cbranch_scc0 .Lmla_q1_newmax
